# adds: norm_g loads of the FINISH-chunk tail hoisted (phase 3); GEMM prologues issue K-tile 1 loads before waiting for K-tile 0
# speedup vs baseline: 1.0073x; 1.0027x over previous
.LBB0_252:
	s_add_u32 s10, s21, s10
	s_addc_u32 s11, s20, s11
	s_lshl_b32 s20, s22, 5
	s_and_b32 s22, s20, 0x60
	s_add_i32 m0, s43, 0x18000
	v_lshl_add_u64 v[8:9], v[8:9], 0, s[84:85]
	s_lshl_b32 s19, s15, 13
	s_lshl_b32 s23, s22, 7
	global_load_lds_dwordx4 v[8:9], off
	v_lshl_add_u64 v[6:7], v[6:7], 0, s[84:85]
	s_add_i32 m0, s43, 0x1a000
	s_add_i32 s54, s43, 0x8000
	s_add_i32 s55, s43, 0xa000
	global_load_lds_dwordx4 v[6:7], off
	v_lshl_add_u64 v[2:3], v[2:3], 0, s[84:85]
	s_mov_b32 m0, s54
	s_add_u32 s20, s46, 0x80080
	global_load_lds_dwordx4 v[2:3], off
	v_lshl_add_u64 v[2:3], v[4:5], 0, s[84:85]
	s_mov_b32 m0, s55
	s_addc_u32 s21, s47, 0
	global_load_lds_dwordx4 v[2:3], off
	s_add_i32 m0, s43, 0x1c000
	v_lshl_add_u64 v[2:3], s[20:21], 0, v[172:173]
	global_load_lds_dwordx4 v[2:3], off
	v_lshl_add_u64 v[2:3], s[20:21], 0, v[154:155]
	s_add_i32 m0, s43, 0x1e000
	s_cmpk_lt_u32 s14, 0x100
	global_load_lds_dwordx4 v[2:3], off
	s_waitcnt vmcnt(8)
	s_barrier
	v_lshrrev_b32_e32 v3, 1, v10
	v_and_b32_e32 v3, 24, v3
	v_and_b32_e32 v2, 15, v10
	v_lshlrev_b32_e32 v4, 1, v3
	v_lshl_or_b32 v162, s15, 6, v2
	v_lshl_or_b32 v2, v2, 6, v4
	v_lshlrev_b32_e32 v4, 2, v10
	v_and_b32_e32 v4, 32, v4
	v_bitop3_b32 v5, v2, s19, v4 bitop3:0xde
	v_bitop3_b32 v163, v2, s23, v4 bitop3:0xde
	v_lshlrev_b32_e32 v2, 15, v11
	v_and_b32_e32 v2, 0xffff0000, v2
	v_or_b32_e32 v164, s22, v3
	v_lshl_add_u32 v2, v12, 12, v2
	v_and_b32_e32 v3, 1, v11
	v_lshl_or_b32 v2, v3, 6, v2
	v_lshl_add_u32 v156, v13, 1, v2
	v_lshlrev_b32_e32 v2, 15, v14
	v_and_b32_e32 v2, 0xffff0000, v2
	s_waitcnt vmcnt(6)
	v_lshl_add_u32 v2, v15, 12, v2
	v_and_b32_e32 v3, 1, v14
	v_lshl_or_b32 v2, v3, 6, v2
	s_cselect_b64 s[14:15], -1, 0
	v_mov_b32_e32 v157, v173
	v_lshl_add_u32 v158, v16, 1, v2
	v_mov_b32_e32 v159, v173
	s_mov_b32 s56, 0
	v_add_u32_e32 v165, 0, v5
	s_barrier
	s_branch .LBB0_255

.LBB0_829:
	v_lshlrev_b32_e32 v68, 2, v83
	v_bfe_u32 v66, v83, 2, 2
	v_and_b32_e32 v67, 16, v83
	v_and_b32_e32 v68, 12, v68
	v_lshl_or_b32 v66, v131, 3, v66
	v_or3_b32 v67, v67, v68, s96
	v_lshlrev_b32_e32 v67, 1, v67
	v_mul_u32_u24_e32 v66, 0x210, v66
	v_add_u32_e32 v157, 0, v84
	v_add3_u32 v66, 0, v67, v66
	v_mad_u32_u24 v156, v154, s86, v157
	s_waitcnt lgkmcnt(0)
	s_barrier
	v_add_u32_e32 v67, 0xf400, v66
	ds_read_b64_tr_b16 v[130:131], v66 offset:62464
	ds_read_b64_tr_b16 v[132:133], v66 offset:64576
	ds_read_b64_tr_b16 v[126:127], v67 offset:8448
	ds_read_b64_tr_b16 v[128:129], v67 offset:10560
	ds_read_b64_tr_b16 v[122:123], v67 offset:16896
	ds_read_b64_tr_b16 v[124:125], v67 offset:19008
	ds_read_b64_tr_b16 v[118:119], v67 offset:25344
	ds_read_b64_tr_b16 v[120:121], v67 offset:27456
	ds_read_b128 v[82:85], v156 offset:53248
	s_waitcnt lgkmcnt(0)
	v_mfma_f32_32x32x16_bf16 v[66:81], v[82:85], v[130:133], 0
	ds_read_b128 v[82:85], v156 offset:53280
	s_movk_i32 s0, 0x110
	v_mad_u32_u24 v166, v154, s0, v157
	v_add_u32_e32 v157, 0x19000, v157
	v_readlane_b32 s0, v244, 17
	s_waitcnt lgkmcnt(0)
	v_mfma_f32_32x32x16_bf16 v[66:81], v[82:85], v[126:129], v[66:81]
	ds_read_b128 v[82:85], v156 offset:53312
	s_waitcnt lgkmcnt(0)
	v_mfma_f32_32x32x16_bf16 v[66:81], v[82:85], v[122:125], v[66:81]
	ds_read_b128 v[82:85], v156 offset:53344
	s_waitcnt lgkmcnt(0)
	v_mfma_f32_32x32x16_bf16 v[66:81], v[82:85], v[118:121], v[66:81]
	v_cvt_pk_bf16_f32 v82, v2, v3
	v_cvt_pk_bf16_f32 v83, v4, v5
	v_cvt_pk_bf16_f32 v84, v6, v7
	v_cvt_pk_bf16_f32 v85, v8, v9
	ds_read_b128 v[86:89], v166
	s_waitcnt lgkmcnt(0)
	v_mfma_f32_32x32x16_bf16 v[66:81], v[86:89], v[82:85], v[66:81]
	v_cvt_pk_bf16_f32 v82, v10, v11
	v_cvt_pk_bf16_f32 v83, v12, v13
	v_cvt_pk_bf16_f32 v84, v14, v15
	v_cvt_pk_bf16_f32 v85, v16, v17
	ds_read_b128 v[86:89], v166 offset:32
	s_waitcnt lgkmcnt(0)
	v_mfma_f32_32x32x16_bf16 v[66:81], v[86:89], v[82:85], v[66:81]
	v_cvt_pk_bf16_f32 v82, v18, v19
	v_cvt_pk_bf16_f32 v83, v20, v21
	v_cvt_pk_bf16_f32 v84, v22, v23
	v_cvt_pk_bf16_f32 v85, v24, v25
	ds_read_b128 v[86:89], v166 offset:64
	s_waitcnt lgkmcnt(0)
	v_mfma_f32_32x32x16_bf16 v[66:81], v[86:89], v[82:85], v[66:81]
	v_cvt_pk_bf16_f32 v82, v26, v27
	v_cvt_pk_bf16_f32 v83, v28, v29
	v_cvt_pk_bf16_f32 v84, v30, v31
	v_cvt_pk_bf16_f32 v85, v32, v33
	ds_read_b128 v[86:89], v166 offset:96
	s_waitcnt lgkmcnt(0)
	v_mfma_f32_32x32x16_bf16 v[66:81], v[86:89], v[82:85], v[66:81]
	v_cvt_pk_bf16_f32 v82, v34, v35
	v_cvt_pk_bf16_f32 v83, v36, v37
	v_cvt_pk_bf16_f32 v84, v38, v39
	v_cvt_pk_bf16_f32 v85, v40, v41
	ds_read_b128 v[86:89], v166 offset:128
	s_waitcnt lgkmcnt(0)
	v_mfma_f32_32x32x16_bf16 v[66:81], v[86:89], v[82:85], v[66:81]
	v_cvt_pk_bf16_f32 v82, v42, v43
	v_cvt_pk_bf16_f32 v83, v44, v45
	v_cvt_pk_bf16_f32 v84, v46, v47
	v_cvt_pk_bf16_f32 v85, v48, v49
	ds_read_b128 v[86:89], v166 offset:160
	s_waitcnt lgkmcnt(0)
	v_mfma_f32_32x32x16_bf16 v[66:81], v[86:89], v[82:85], v[66:81]
	v_cvt_pk_bf16_f32 v82, v50, v51
	v_cvt_pk_bf16_f32 v83, v52, v53
	v_cvt_pk_bf16_f32 v84, v54, v55
	v_cvt_pk_bf16_f32 v85, v56, v57
	ds_read_b128 v[86:89], v166 offset:192
	s_waitcnt lgkmcnt(0)
	v_mfma_f32_32x32x16_bf16 v[66:81], v[86:89], v[82:85], v[66:81]
	v_cvt_pk_bf16_f32 v82, v58, v59
	v_cvt_pk_bf16_f32 v83, v60, v61
	v_cvt_pk_bf16_f32 v84, v62, v63
	v_cvt_pk_bf16_f32 v85, v64, v65
	ds_read_b128 v[86:89], v166 offset:224
	s_waitcnt lgkmcnt(0)
	v_mfma_f32_32x32x16_bf16 v[66:81], v[86:89], v[82:85], v[66:81]
	s_nop 0
	s_nop 7
	s_nop 3
	ds_read_b128 v[158:161], v156 offset:57856
	s_waitcnt lgkmcnt(0)
	v_mfma_f32_32x32x16_bf16 v[82:97], v[158:161], v[130:133], 0
	ds_read_b128 v[158:161], v156 offset:57888
	s_waitcnt lgkmcnt(0)
	v_mfma_f32_32x32x16_bf16 v[82:97], v[158:161], v[126:129], v[82:97]
	ds_read_b128 v[158:161], v156 offset:57920
	s_waitcnt lgkmcnt(0)
	v_mfma_f32_32x32x16_bf16 v[82:97], v[158:161], v[122:125], v[82:97]
	ds_read_b128 v[158:161], v156 offset:57952
	s_waitcnt lgkmcnt(0)
	v_mfma_f32_32x32x16_bf16 v[82:97], v[158:161], v[118:121], v[82:97]
	v_cvt_pk_bf16_f32 v158, v2, v3
	v_cvt_pk_bf16_f32 v159, v4, v5
	v_cvt_pk_bf16_f32 v160, v6, v7
	v_cvt_pk_bf16_f32 v161, v8, v9
	ds_read_b128 v[162:165], v166 offset:8704
	s_waitcnt lgkmcnt(0)
	v_mfma_f32_32x32x16_bf16 v[82:97], v[162:165], v[158:161], v[82:97]
	v_cvt_pk_bf16_f32 v158, v10, v11
	v_cvt_pk_bf16_f32 v159, v12, v13
	v_cvt_pk_bf16_f32 v160, v14, v15
	v_cvt_pk_bf16_f32 v161, v16, v17
	ds_read_b128 v[162:165], v166 offset:8736
	s_waitcnt lgkmcnt(0)
	v_mfma_f32_32x32x16_bf16 v[82:97], v[162:165], v[158:161], v[82:97]
	v_cvt_pk_bf16_f32 v158, v18, v19
	v_cvt_pk_bf16_f32 v159, v20, v21
	v_cvt_pk_bf16_f32 v160, v22, v23
	v_cvt_pk_bf16_f32 v161, v24, v25
	ds_read_b128 v[162:165], v166 offset:8768
	s_waitcnt lgkmcnt(0)
	v_mfma_f32_32x32x16_bf16 v[82:97], v[162:165], v[158:161], v[82:97]
	v_cvt_pk_bf16_f32 v158, v26, v27
	v_cvt_pk_bf16_f32 v159, v28, v29
	v_cvt_pk_bf16_f32 v160, v30, v31
	v_cvt_pk_bf16_f32 v161, v32, v33
	ds_read_b128 v[162:165], v166 offset:8800
	s_waitcnt lgkmcnt(0)
	v_mfma_f32_32x32x16_bf16 v[82:97], v[162:165], v[158:161], v[82:97]
	v_cvt_pk_bf16_f32 v158, v34, v35
	v_cvt_pk_bf16_f32 v159, v36, v37
	v_cvt_pk_bf16_f32 v160, v38, v39
	v_cvt_pk_bf16_f32 v161, v40, v41
	ds_read_b128 v[162:165], v166 offset:8832
	s_waitcnt lgkmcnt(0)
	v_mfma_f32_32x32x16_bf16 v[82:97], v[162:165], v[158:161], v[82:97]
	v_cvt_pk_bf16_f32 v158, v42, v43
	v_cvt_pk_bf16_f32 v159, v44, v45
	v_cvt_pk_bf16_f32 v160, v46, v47
	v_cvt_pk_bf16_f32 v161, v48, v49
	ds_read_b128 v[162:165], v166 offset:8864
	s_waitcnt lgkmcnt(0)
	v_mfma_f32_32x32x16_bf16 v[82:97], v[162:165], v[158:161], v[82:97]
	v_cvt_pk_bf16_f32 v158, v50, v51
	v_cvt_pk_bf16_f32 v159, v52, v53
	v_cvt_pk_bf16_f32 v160, v54, v55
	v_cvt_pk_bf16_f32 v161, v56, v57
	ds_read_b128 v[162:165], v166 offset:8896
	s_waitcnt lgkmcnt(0)
	v_mfma_f32_32x32x16_bf16 v[82:97], v[162:165], v[158:161], v[82:97]
	v_cvt_pk_bf16_f32 v158, v58, v59
	v_cvt_pk_bf16_f32 v159, v60, v61
	v_cvt_pk_bf16_f32 v160, v62, v63
	v_cvt_pk_bf16_f32 v161, v64, v65
	ds_read_b128 v[162:165], v166 offset:8928
	s_waitcnt lgkmcnt(0)
	v_mfma_f32_32x32x16_bf16 v[82:97], v[162:165], v[158:161], v[82:97]
	s_nop 0
	s_nop 7
	s_nop 3
	ds_read_b128 v[158:161], v157
	ds_read_b128 v[162:165], v157 offset:32
	ds_read_b128 v[166:169], v157 offset:64
	ds_read_b128 v[178:181], v157 offset:96
	s_waitcnt lgkmcnt(3)
	v_pk_mul_f32 v[2:3], v[2:3], v[158:159]
	v_pk_mul_f32 v[4:5], v[4:5], v[160:161]
	ds_read_b128 v[158:161], v156 offset:34816
	s_waitcnt lgkmcnt(1)
	v_pk_mul_f32 v[14:15], v[14:15], v[178:179]
	v_pk_mul_f32 v[10:11], v[10:11], v[166:167]
	v_pk_mul_f32 v[6:7], v[6:7], v[162:163]
	v_pk_mul_f32 v[16:17], v[16:17], v[180:181]
	v_pk_mul_f32 v[12:13], v[12:13], v[168:169]
	v_pk_mul_f32 v[8:9], v[8:9], v[164:165]
	s_waitcnt lgkmcnt(0)
	s_nop 0
	v_mfma_f32_32x32x16_bf16 v[2:17], v[158:161], v[130:133], v[2:17]
	ds_read_b128 v[158:161], v156 offset:34848
	s_waitcnt lgkmcnt(0)
	v_mfma_f32_32x32x16_bf16 v[2:17], v[158:161], v[126:129], v[2:17]
	ds_read_b128 v[158:161], v156 offset:34880
	s_waitcnt lgkmcnt(0)
	v_mfma_f32_32x32x16_bf16 v[2:17], v[158:161], v[122:125], v[2:17]
	ds_read_b128 v[158:161], v156 offset:34912
	s_waitcnt lgkmcnt(0)
	v_mfma_f32_32x32x16_bf16 v[2:17], v[158:161], v[118:121], v[2:17]
	s_nop 0
	s_nop 7
	s_nop 3
	ds_read_b128 v[158:161], v157 offset:128
	ds_read_b128 v[162:165], v157 offset:160
	ds_read_b128 v[166:169], v157 offset:192
	ds_read_b128 v[178:181], v157 offset:224
	s_waitcnt lgkmcnt(3)
	v_pk_mul_f32 v[18:19], v[18:19], v[158:159]
	v_pk_mul_f32 v[20:21], v[20:21], v[160:161]
	ds_read_b128 v[158:161], v156 offset:39424
	s_waitcnt lgkmcnt(1)
	v_pk_mul_f32 v[30:31], v[30:31], v[178:179]
	v_pk_mul_f32 v[26:27], v[26:27], v[166:167]
	v_pk_mul_f32 v[22:23], v[22:23], v[162:163]
	v_pk_mul_f32 v[32:33], v[32:33], v[180:181]
	v_pk_mul_f32 v[28:29], v[28:29], v[168:169]
	v_pk_mul_f32 v[24:25], v[24:25], v[164:165]
	s_waitcnt lgkmcnt(0)
	s_nop 0
	v_mfma_f32_32x32x16_bf16 v[18:33], v[158:161], v[130:133], v[18:33]
	ds_read_b128 v[158:161], v156 offset:39456
	s_waitcnt lgkmcnt(0)
	v_mfma_f32_32x32x16_bf16 v[18:33], v[158:161], v[126:129], v[18:33]
	ds_read_b128 v[158:161], v156 offset:39488
	s_waitcnt lgkmcnt(0)
	v_mfma_f32_32x32x16_bf16 v[18:33], v[158:161], v[122:125], v[18:33]
	ds_read_b128 v[158:161], v156 offset:39520
	s_waitcnt lgkmcnt(0)
	v_mfma_f32_32x32x16_bf16 v[18:33], v[158:161], v[118:121], v[18:33]
	s_nop 0
	s_nop 7
	s_nop 3
	ds_read_b128 v[158:161], v157 offset:256
	ds_read_b128 v[162:165], v157 offset:288
	ds_read_b128 v[166:169], v157 offset:320
	ds_read_b128 v[178:181], v157 offset:352
	s_waitcnt lgkmcnt(3)
	v_pk_mul_f32 v[34:35], v[34:35], v[158:159]
	v_pk_mul_f32 v[36:37], v[36:37], v[160:161]
	ds_read_b128 v[158:161], v156 offset:44032
	s_waitcnt lgkmcnt(1)
	v_pk_mul_f32 v[46:47], v[46:47], v[178:179]
	v_pk_mul_f32 v[42:43], v[42:43], v[166:167]
	v_pk_mul_f32 v[38:39], v[38:39], v[162:163]
	v_pk_mul_f32 v[48:49], v[48:49], v[180:181]
	v_pk_mul_f32 v[44:45], v[44:45], v[168:169]
	v_pk_mul_f32 v[40:41], v[40:41], v[164:165]
	s_waitcnt lgkmcnt(0)
	s_nop 0
	v_mfma_f32_32x32x16_bf16 v[34:49], v[158:161], v[130:133], v[34:49]
	ds_read_b128 v[158:161], v156 offset:44064
	s_waitcnt lgkmcnt(0)
	v_mfma_f32_32x32x16_bf16 v[34:49], v[158:161], v[126:129], v[34:49]
	ds_read_b128 v[158:161], v156 offset:44096
	s_waitcnt lgkmcnt(0)
	v_mfma_f32_32x32x16_bf16 v[34:49], v[158:161], v[122:125], v[34:49]
	ds_read_b128 v[158:161], v156 offset:44128
	s_waitcnt lgkmcnt(0)
	v_mfma_f32_32x32x16_bf16 v[34:49], v[158:161], v[118:121], v[34:49]
	s_nop 0
	s_nop 7
	s_nop 3
	ds_read_b128 v[158:161], v157 offset:384
	ds_read_b128 v[162:165], v157 offset:416
	ds_read_b128 v[166:169], v157 offset:448
	ds_read_b128 v[178:181], v157 offset:480
	s_waitcnt lgkmcnt(3)
	v_pk_mul_f32 v[50:51], v[50:51], v[158:159]
	v_pk_mul_f32 v[52:53], v[52:53], v[160:161]
	ds_read_b128 v[158:161], v156 offset:48640
	s_waitcnt lgkmcnt(1)
	v_pk_mul_f32 v[62:63], v[62:63], v[178:179]
	v_pk_mul_f32 v[58:59], v[58:59], v[166:167]
	v_pk_mul_f32 v[54:55], v[54:55], v[162:163]
	v_pk_mul_f32 v[64:65], v[64:65], v[180:181]
	v_pk_mul_f32 v[60:61], v[60:61], v[168:169]
	v_pk_mul_f32 v[56:57], v[56:57], v[164:165]
	s_waitcnt lgkmcnt(0)
	s_nop 0
	v_mfma_f32_32x32x16_bf16 v[50:65], v[158:161], v[130:133], v[50:65]
	ds_read_b128 v[130:133], v156 offset:48672
	s_waitcnt lgkmcnt(0)
	v_mfma_f32_32x32x16_bf16 v[50:65], v[130:133], v[126:129], v[50:65]
	ds_read_b128 v[126:129], v156 offset:48704
	s_waitcnt lgkmcnt(0)
	v_mfma_f32_32x32x16_bf16 v[50:65], v[126:129], v[122:125], v[50:65]
	ds_read_b128 v[122:125], v156 offset:48736
	s_waitcnt lgkmcnt(0)
	v_mfma_f32_32x32x16_bf16 v[50:65], v[122:125], v[118:121], v[50:65]
	v_lshlrev_b32_e32 v118, 2, v154
	v_mul_i32_i24_e32 v119, 0x410, v155
	v_add3_u32 v118, s0, v118, v119
	s_movk_i32 s0, 0x410
	s_nop 7
	s_nop 3
	s_barrier
	ds_write_b32 v118, v66
	ds_write_b32 v118, v67 offset:1040
	ds_write_b32 v118, v68 offset:2080
	ds_write_b32 v118, v69 offset:3120
	ds_write_b32 v118, v70 offset:8320
	ds_write_b32 v118, v71 offset:9360
	ds_write_b32 v118, v72 offset:10400
	ds_write_b32 v118, v73 offset:11440
	ds_write_b32 v118, v74 offset:16640
	ds_write_b32 v118, v75 offset:17680
	ds_write_b32 v118, v76 offset:18720
	ds_write_b32 v118, v77 offset:19760
	ds_write_b32 v118, v78 offset:24960
	ds_write_b32 v118, v79 offset:26000
	ds_write_b32 v118, v80 offset:27040
	ds_write_b32 v118, v81 offset:28080
	ds_write_b32 v118, v82 offset:33280
	ds_write_b32 v118, v83 offset:34320
	ds_write_b32 v118, v84 offset:35360
	ds_write_b32 v118, v85 offset:36400
	ds_write_b32 v118, v86 offset:41600
	ds_write_b32 v118, v87 offset:42640
	ds_write_b32 v118, v88 offset:43680
	ds_write_b32 v118, v89 offset:44720
	ds_write_b32 v118, v90 offset:49920
	ds_write_b32 v118, v91 offset:50960
	ds_write_b32 v118, v92 offset:52000
	ds_write_b32 v118, v93 offset:53040
	ds_write_b32 v118, v94 offset:58240
	ds_write_b32 v118, v95 offset:59280
	ds_write_b32 v118, v96 offset:60320
	ds_write_b32 v118, v97 offset:61360
	v_lshlrev_b32_e32 v66, 7, v151
	v_mul_lo_u32 v67, v150, s0
	v_add3_u32 v123, 0, v66, v67
	s_waitcnt lgkmcnt(0)
	s_barrier
	ds_read_b128 v[94:97], v123
	ds_read_b128 v[90:93], v123 offset:16
	ds_read_b128 v[86:89], v123 offset:32
	ds_read_b128 v[82:85], v123 offset:48
	ds_read_b128 v[78:81], v123 offset:64
	ds_read_b128 v[74:77], v123 offset:80
	s_waitcnt lgkmcnt(5)
	v_mov_b32_e32 v66, v94
	s_waitcnt lgkmcnt(4)
	v_mov_b32_e32 v67, v90
	v_mov_b32_e32 v68, v95
	v_mov_b32_e32 v69, v91
	v_pk_add_f32 v[66:67], v[66:67], v[68:69]
	v_mov_b32_e32 v68, v96
	v_mov_b32_e32 v69, v92
	v_mov_b32_e32 v70, v97
	v_mov_b32_e32 v71, v93
	v_pk_add_f32 v[68:69], v[68:69], v[70:71]
	s_waitcnt lgkmcnt(3)
	v_mov_b32_e32 v70, v86
	v_pk_add_f32 v[66:67], v[66:67], v[68:69]
	v_mov_b32_e32 v68, v87
	v_mov_b32_e32 v69, v88
	v_mov_b32_e32 v71, v89
	v_pk_add_f32 v[68:69], v[68:69], v[70:71]
	v_add_f32_e32 v66, 0, v66
	v_pk_add_f32 v[68:69], v[68:69], v[68:69] op_sel:[0,1] op_sel_hi:[1,0]
	v_add_f32_e32 v66, v66, v67
	s_waitcnt lgkmcnt(2)
	v_add_f32_e32 v70, v82, v83
	v_add_f32_e32 v72, v84, v85
	s_waitcnt lgkmcnt(1)
	v_mov_b32_e32 v67, v78
	v_mov_b32_e32 v69, v79
	v_mov_b32_e32 v71, v80
	v_mov_b32_e32 v73, v81
	v_pk_add_f32 v[66:67], v[66:67], v[68:69]
	v_pk_add_f32 v[68:69], v[70:71], v[72:73]
	ds_read_b128 v[70:73], v123 offset:96
	v_pk_add_f32 v[66:67], v[66:67], v[68:69]
	s_waitcnt lgkmcnt(1)
	v_mov_b32_e32 v68, v74
	v_pk_add_f32 v[118:119], v[66:67], v[66:67] op_sel:[0,1] op_sel_hi:[1,0]
	v_mov_b32_e32 v66, v75
	v_mov_b32_e32 v67, v76
	v_mov_b32_e32 v69, v77
	v_pk_add_f32 v[66:67], v[66:67], v[68:69]
	s_nop 0
	v_pk_add_f32 v[120:121], v[66:67], v[66:67] op_sel:[0,1] op_sel_hi:[1,0]
	ds_read_b128 v[66:69], v123 offset:112
	s_waitcnt lgkmcnt(1)
	v_add_f32_e32 v122, v70, v71
	v_add_f32_e32 v124, v72, v73
	s_waitcnt lgkmcnt(0)
	v_mov_b32_e32 v119, v66
	v_mov_b32_e32 v121, v67
	v_mov_b32_e32 v123, v68
	v_mov_b32_e32 v125, v69
	v_pk_add_f32 v[118:119], v[118:119], v[120:121]
	v_pk_add_f32 v[120:121], v[122:123], v[124:125]
	s_nop 0
	v_pk_add_f32 v[118:119], v[118:119], v[120:121]
	v_and_b32_e32 v120, 64, v203
	v_add_f32_e32 v118, v118, v119
	v_xor_b32_e32 v119, 1, v203
	v_add_u32_e32 v121, 64, v120
	v_cmp_lt_i32_e32 vcc, v119, v121
	s_nop 1
	v_cndmask_b32_e32 v119, v203, v119, vcc
	v_lshlrev_b32_e32 v120, 2, v119
	ds_bpermute_b32 v119, v120, v118
	s_waitcnt lgkmcnt(0)
	v_add_f32_e32 v118, v118, v119
	v_xor_b32_e32 v119, 2, v203
	v_cmp_lt_i32_e32 vcc, v119, v121
	s_nop 1
	v_cndmask_b32_e32 v119, v203, v119, vcc
	v_lshlrev_b32_e32 v122, 2, v119
	ds_bpermute_b32 v119, v122, v118
	s_waitcnt lgkmcnt(0)
	v_add_f32_e32 v118, v118, v119
	v_xor_b32_e32 v119, 4, v203
	v_cmp_lt_i32_e32 vcc, v119, v121
	s_nop 1
	v_cndmask_b32_e32 v119, v203, v119, vcc
	v_lshlrev_b32_e32 v121, 2, v119
	ds_bpermute_b32 v119, v121, v118
	s_waitcnt lgkmcnt(0)
	v_add_f32_e32 v123, v118, v119
	v_fmamk_f32 v97, v123, 0xbb800000, v97
	v_fmamk_f32 v95, v123, 0xbb800000, v95
	v_fmamk_f32 v96, v123, 0xbb800000, v96
	v_fmac_f32_e32 v94, 0xbb800000, v123
	v_mul_f32_e32 v118, v95, v95
	v_mul_f32_e32 v119, v97, v97
	v_fmac_f32_e32 v118, v94, v94
	v_fmac_f32_e32 v119, v96, v96
	v_add_f32_e32 v124, v118, v119
	v_fmamk_f32 v119, v123, 0xbb800000, v93
	v_fmamk_f32 v91, v123, 0xbb800000, v91
	v_fmamk_f32 v118, v123, 0xbb800000, v92
	v_fmac_f32_e32 v90, 0xbb800000, v123
	v_mul_f32_e32 v92, v91, v91
	v_mul_f32_e32 v93, v119, v119
	v_fmac_f32_e32 v92, v90, v90
	v_fmac_f32_e32 v93, v118, v118
	v_add_f32_e32 v92, v92, v93
	v_fmamk_f32 v89, v123, 0xbb800000, v89
	v_fmamk_f32 v87, v123, 0xbb800000, v87
	v_add_f32_e32 v92, v124, v92
	v_fmamk_f32 v88, v123, 0xbb800000, v88
	v_fmac_f32_e32 v86, 0xbb800000, v123
	v_mul_f32_e32 v93, v87, v87
	v_mul_f32_e32 v124, v89, v89
	v_fmac_f32_e32 v93, v86, v86
	v_fmac_f32_e32 v124, v88, v88
	v_add_f32_e32 v93, v93, v124
	v_fmamk_f32 v85, v123, 0xbb800000, v85
	v_fmamk_f32 v83, v123, 0xbb800000, v83
	v_add_f32_e32 v92, v93, v92
	v_fmamk_f32 v84, v123, 0xbb800000, v84
	v_fmac_f32_e32 v82, 0xbb800000, v123
	v_mul_f32_e32 v93, v83, v83
	v_mul_f32_e32 v124, v85, v85
	v_fmac_f32_e32 v93, v82, v82
	v_fmac_f32_e32 v124, v84, v84
	v_add_f32_e32 v93, v93, v124
	v_fmamk_f32 v81, v123, 0xbb800000, v81
	v_fmamk_f32 v79, v123, 0xbb800000, v79
	v_add_f32_e32 v92, v93, v92
	v_fmamk_f32 v80, v123, 0xbb800000, v80
	v_fmac_f32_e32 v78, 0xbb800000, v123
	v_mul_f32_e32 v93, v79, v79
	v_mul_f32_e32 v124, v81, v81
	v_fmac_f32_e32 v93, v78, v78
	v_fmac_f32_e32 v124, v80, v80
	v_add_f32_e32 v93, v93, v124
	v_fmamk_f32 v77, v123, 0xbb800000, v77
	v_fmamk_f32 v75, v123, 0xbb800000, v75
	v_add_f32_e32 v92, v93, v92
	v_fmamk_f32 v76, v123, 0xbb800000, v76
	v_fmac_f32_e32 v74, 0xbb800000, v123
	v_mul_f32_e32 v93, v75, v75
	v_mul_f32_e32 v124, v77, v77
	v_fmac_f32_e32 v93, v74, v74
	v_fmac_f32_e32 v124, v76, v76
	v_add_f32_e32 v93, v93, v124
	v_fmamk_f32 v73, v123, 0xbb800000, v73
	v_fmamk_f32 v71, v123, 0xbb800000, v71
	v_add_f32_e32 v92, v93, v92
	v_fmamk_f32 v72, v123, 0xbb800000, v72
	v_fmac_f32_e32 v70, 0xbb800000, v123
	v_mul_f32_e32 v93, v71, v71
	v_mul_f32_e32 v124, v73, v73
	v_fmac_f32_e32 v93, v70, v70
	v_fmac_f32_e32 v124, v72, v72
	v_add_f32_e32 v93, v93, v124
	v_fmamk_f32 v69, v123, 0xbb800000, v69
	v_fmamk_f32 v67, v123, 0xbb800000, v67
	v_add_f32_e32 v92, v93, v92
	v_fmamk_f32 v68, v123, 0xbb800000, v68
	v_fmac_f32_e32 v66, 0xbb800000, v123
	v_mul_f32_e32 v93, v67, v67
	v_mul_f32_e32 v123, v69, v69
	v_fmac_f32_e32 v93, v66, v66
	v_fmac_f32_e32 v123, v68, v68
	v_add_f32_e32 v93, v93, v123
	v_add_f32_e32 v92, v93, v92
	ds_bpermute_b32 v93, v120, v92
	s_waitcnt lgkmcnt(0)
	v_add_f32_e32 v92, v92, v93
	ds_bpermute_b32 v93, v122, v92
	s_waitcnt lgkmcnt(0)
	v_add_f32_e32 v92, v92, v93
	ds_bpermute_b32 v93, v121, v92
	s_and_saveexec_b64 s[18:19], s[38:39]
	s_cbranch_execz .LBB0_780
	s_waitcnt lgkmcnt(0)
	v_add_f32_e32 v92, v92, v93
	v_fmamk_f32 v92, v92, 0x3b800000, v171
	v_cmp_gt_f32_e32 vcc, s9, v92
	v_mul_f32_e32 v93, 0x4f800000, v92
	v_lshlrev_b32_e32 v122, 5, v151
	v_cndmask_b32_e32 v92, v92, v93, vcc
	v_sqrt_f32_e32 v93, v92
	v_ashrrev_i32_e32 v151, 31, v150
	v_lshlrev_b32_e32 v132, 16, v114
	v_and_b32_e32 v133, 0xffff0000, v114
	v_add_u32_e32 v120, -1, v93
	v_fma_f32 v121, -v120, v93, v92
	v_cmp_ge_f32_e64 s[0:1], 0, v121
	v_add_u32_e32 v121, 1, v93
	v_lshlrev_b32_e32 v114, 16, v116
	v_cndmask_b32_e64 v120, v93, v120, s[0:1]
	v_fma_f32 v93, -v121, v93, v92
	v_cmp_lt_f32_e64 s[0:1], 0, v93
	s_nop 1
	v_cndmask_b32_e64 v93, v120, v121, s[0:1]
	v_mul_f32_e32 v120, 0x37800000, v93
	v_cndmask_b32_e32 v93, v93, v120, vcc
	v_cmp_class_f32_e32 vcc, v92, v200
	s_nop 1
	v_cndmask_b32_e32 v92, v93, v92, vcc
	v_div_scale_f32 v93, s[0:1], v92, v92, 1.0
	v_rcp_f32_e32 v120, v93
	v_readlane_b32 s0, v242, 48
	v_readlane_b32 s1, v242, 49
	v_fma_f32 v121, -v93, v120, 1.0
	v_fmac_f32_e32 v120, v121, v120
	v_div_scale_f32 v121, vcc, 1.0, v92, 1.0
	v_mul_f32_e32 v123, v121, v120
	v_fma_f32 v124, -v93, v123, v121
	v_fmac_f32_e32 v123, v124, v120
	v_fma_f32 v93, -v93, v123, v121
	v_div_fmas_f32 v93, v93, v120, v123
	v_div_fixup_f32 v92, v93, v92, 1.0
	v_or_b32_e32 v93, s21, v122
	v_lshlrev_b32_e32 v172, 2, v93
	v_lshl_add_u64 v[120:121], s[88:89], 0, v[150:151]
	v_lshl_add_u64 v[122:123], s[22:23], 0, v[172:173]
	v_lshlrev_b32_e32 v172, 1, v93
	v_lshl_add_u64 v[124:125], s[0:1], 0, v[172:173]
	v_lshlrev_b64 v[120:121], 11, v[120:121]
	v_lshl_add_u64 v[120:121], v[124:125], 0, v[120:121]
	global_load_dwordx4 v[204:207], v[122:123], off
	global_load_dwordx4 v[208:211], v[122:123], off offset:16
	global_load_dwordx4 v[212:215], v[122:123], off offset:32
	global_load_dwordx4 v[216:219], v[122:123], off offset:48
	global_load_dwordx4 v[220:223], v[122:123], off offset:64
	global_load_dwordx4 v[224:227], v[122:123], off offset:80
	global_load_dwordx4 v[228:231], v[122:123], off offset:96
	global_load_dwordx4 v[232:235], v[122:123], off offset:112
	s_nop 0
	v_pk_mul_f32 v[96:97], v[96:97], v[92:93] op_sel_hi:[1,0]
	v_pk_mul_f32 v[94:95], v[94:95], v[92:93] op_sel_hi:[1,0]
	v_lshlrev_b32_e32 v150, 16, v115
	v_and_b32_e32 v151, 0xffff0000, v115
	v_pk_mul_f32 v[118:119], v[118:119], v[92:93] op_sel_hi:[1,0]
	v_pk_mul_f32 v[90:91], v[90:91], v[92:93] op_sel_hi:[1,0]
	v_and_b32_e32 v115, 0xffff0000, v116
	v_lshlrev_b32_e32 v116, 16, v117
	v_and_b32_e32 v117, 0xffff0000, v117
	v_pk_mul_f32 v[86:87], v[86:87], v[92:93] op_sel_hi:[1,0]
	v_pk_mul_f32 v[84:85], v[84:85], v[92:93] op_sel_hi:[1,0]
	v_pk_mul_f32 v[82:83], v[82:83], v[92:93] op_sel_hi:[1,0]
	v_pk_mul_f32 v[88:89], v[88:89], v[92:93] op_sel_hi:[1,0]
	v_pk_mul_f32 v[76:77], v[76:77], v[92:93] op_sel_hi:[1,0]
	v_pk_mul_f32 v[74:75], v[74:75], v[92:93] op_sel_hi:[1,0]
	v_pk_mul_f32 v[80:81], v[80:81], v[92:93] op_sel_hi:[1,0]
	v_pk_mul_f32 v[78:79], v[78:79], v[92:93] op_sel_hi:[1,0]
	v_pk_mul_f32 v[68:69], v[68:69], v[92:93] op_sel_hi:[1,0]
	v_pk_mul_f32 v[66:67], v[66:67], v[92:93] op_sel_hi:[1,0]
	v_pk_mul_f32 v[72:73], v[72:73], v[92:93] op_sel_hi:[1,0]
	v_pk_mul_f32 v[70:71], v[70:71], v[92:93] op_sel_hi:[1,0]
	s_waitcnt vmcnt(0) lgkmcnt(0)
	v_pk_mul_f32 v[94:95], v[94:95], v[204:205]
	v_pk_mul_f32 v[96:97], v[96:97], v[206:207]
	v_pk_mul_f32 v[94:95], v[94:95], v[132:133]
	v_pk_mul_f32 v[96:97], v[96:97], v[150:151]
	v_pk_mul_f32 v[90:91], v[90:91], v[208:209]
	v_pk_mul_f32 v[118:119], v[118:119], v[210:211]
	v_pk_mul_f32 v[90:91], v[90:91], v[114:115]
	v_pk_mul_f32 v[116:117], v[118:119], v[116:117]
	v_cvt_pk_bf16_f32 v94, v94, v95
	v_cvt_pk_bf16_f32 v95, v96, v97
	v_cvt_pk_bf16_f32 v96, v90, v91
	v_lshlrev_b32_e32 v90, 16, v110
	v_cvt_pk_bf16_f32 v97, v116, v117
	global_store_dwordx4 v[120:121], v[94:97], off
	v_and_b32_e32 v91, 0xffff0000, v110
	v_lshlrev_b32_e32 v114, 16, v111
	v_and_b32_e32 v115, 0xffff0000, v111
	v_lshlrev_b32_e32 v116, 16, v112
	v_and_b32_e32 v117, 0xffff0000, v112
	v_lshlrev_b32_e32 v118, 16, v113
	v_and_b32_e32 v119, 0xffff0000, v113
	s_nop 0
	s_nop 0
	s_nop 0
	v_pk_mul_f32 v[86:87], v[86:87], v[212:213]
	v_pk_mul_f32 v[82:83], v[82:83], v[216:217]
	v_pk_mul_f32 v[84:85], v[84:85], v[218:219]
	v_pk_mul_f32 v[88:89], v[88:89], v[214:215]
	v_pk_mul_f32 v[86:87], v[86:87], v[90:91]
	v_pk_mul_f32 v[90:91], v[84:85], v[118:119]
	v_pk_mul_f32 v[84:85], v[82:83], v[116:117]
	v_pk_mul_f32 v[88:89], v[88:89], v[114:115]
	v_cvt_pk_bf16_f32 v82, v86, v87
	v_lshlrev_b32_e32 v94, 16, v107
	v_cvt_pk_bf16_f32 v83, v88, v89
	v_cvt_pk_bf16_f32 v84, v84, v85
	v_cvt_pk_bf16_f32 v85, v90, v91
	global_store_dwordx4 v[120:121], v[82:85], off offset:16
	s_nop 0
	s_nop 0
	s_nop 0
	v_lshlrev_b32_e32 v90, 16, v106
	v_and_b32_e32 v91, 0xffff0000, v106
	v_and_b32_e32 v95, 0xffff0000, v107
	v_lshlrev_b32_e32 v96, 16, v108
	v_and_b32_e32 v97, 0xffff0000, v108
	v_lshlrev_b32_e32 v106, 16, v109
	v_and_b32_e32 v107, 0xffff0000, v109
	s_nop 0
	v_pk_mul_f32 v[78:79], v[78:79], v[220:221]
	v_pk_mul_f32 v[74:75], v[74:75], v[224:225]
	v_pk_mul_f32 v[76:77], v[76:77], v[226:227]
	v_pk_mul_f32 v[80:81], v[80:81], v[222:223]
	v_pk_mul_f32 v[82:83], v[76:77], v[106:107]
	v_pk_mul_f32 v[76:77], v[74:75], v[96:97]
	v_pk_mul_f32 v[80:81], v[80:81], v[94:95]
	v_pk_mul_f32 v[78:79], v[78:79], v[90:91]
	v_lshlrev_b32_e32 v86, 16, v104
	v_cvt_pk_bf16_f32 v74, v78, v79
	v_cvt_pk_bf16_f32 v75, v80, v81
	v_cvt_pk_bf16_f32 v76, v76, v77
	v_cvt_pk_bf16_f32 v77, v82, v83
	global_store_dwordx4 v[120:121], v[74:77], off offset:32
	s_nop 0
	s_nop 0
	s_nop 0
	v_and_b32_e32 v87, 0xffff0000, v104
	v_lshlrev_b32_e32 v88, 16, v105
	v_and_b32_e32 v89, 0xffff0000, v105
	v_lshlrev_b32_e32 v82, 16, v102
	v_and_b32_e32 v83, 0xffff0000, v102
	v_lshlrev_b32_e32 v84, 16, v103
	v_and_b32_e32 v85, 0xffff0000, v103
	s_nop 0
	v_pk_mul_f32 v[70:71], v[70:71], v[228:229]
	v_pk_mul_f32 v[66:67], v[66:67], v[232:233]
	v_pk_mul_f32 v[68:69], v[68:69], v[234:235]
	v_pk_mul_f32 v[72:73], v[72:73], v[230:231]
	v_pk_mul_f32 v[74:75], v[68:69], v[88:89]
	v_pk_mul_f32 v[68:69], v[66:67], v[86:87]
	v_pk_mul_f32 v[72:73], v[72:73], v[84:85]
	v_pk_mul_f32 v[70:71], v[70:71], v[82:83]
	s_nop 0
	v_cvt_pk_bf16_f32 v66, v70, v71
	v_cvt_pk_bf16_f32 v67, v72, v73
	v_cvt_pk_bf16_f32 v68, v68, v69
	v_cvt_pk_bf16_f32 v69, v74, v75
	global_store_dwordx4 v[120:121], v[66:69], off offset:48
	s_branch .LBB0_780

.LBB0_892:
	v_lshrrev_b32_e32 v18, 1, v5
	v_lshl_add_u64 v[10:11], s[0:1], 0, v[172:173]
	v_mov_b32_e32 v135, v173
	v_and_b32_e32 v144, 24, v18
	s_lshl_b32 s10, s10, 5
	v_lshl_add_u64 v[12:13], s[0:1], 0, v[134:135]
	v_mov_b32_e32 v139, v173
	v_and_b32_e32 v9, 15, v5
	v_lshlrev_b32_e32 v18, 1, v144
	v_lshlrev_b32_e32 v5, 2, v5
	s_and_b32 s38, s10, 0x60
	s_add_i32 m0, s28, 0x18000
	v_lshl_add_u64 v[10:11], v[10:11], 0, s[84:85]
	v_lshl_add_u64 v[14:15], s[46:47], 0, v[138:139]
	v_mov_b32_e32 v137, v173
	v_lshl_or_b32 v145, s11, 6, v9
	v_lshl_or_b32 v9, v9, 6, v18
	s_lshl_b32 s11, s11, 13
	v_and_b32_e32 v5, 32, v5
	s_lshl_b32 s10, s38, 7
	global_load_lds_dwordx4 v[10:11], off
	v_lshl_add_u64 v[10:11], v[12:13], 0, s[84:85]
	s_add_i32 m0, s28, 0x1a000
	s_add_i32 s39, s28, 0x8000
	s_add_i32 s40, s28, 0xa000
	v_lshl_add_u64 v[16:17], s[46:47], 0, v[136:137]
	v_bitop3_b32 v146, v9, s10, v5 bitop3:0xde
	global_load_lds_dwordx4 v[10:11], off
	v_lshl_add_u64 v[10:11], v[14:15], 0, s[84:85]
	s_mov_b32 m0, s39
	s_add_u32 s10, s0, 0x40080
	v_bitop3_b32 v18, v9, s11, v5 bitop3:0xde
	global_load_lds_dwordx4 v[10:11], off
	v_lshl_add_u64 v[10:11], v[16:17], 0, s[84:85]
	s_mov_b32 m0, s40
	s_addc_u32 s11, s1, 0
	global_load_lds_dwordx4 v[10:11], off
	s_add_i32 m0, s28, 0x1c000
	v_lshl_add_u64 v[10:11], s[10:11], 0, v[172:173]
	global_load_lds_dwordx4 v[10:11], off
	v_lshl_add_u64 v[10:11], s[10:11], 0, v[134:135]
	s_add_i32 m0, s28, 0x1e000
	v_lshlrev_b32_e32 v5, 14, v7
	global_load_lds_dwordx4 v[10:11], off
	s_waitcnt vmcnt(8)
	s_barrier
	v_and_b32_e32 v5, 0xffff8000, v5
	v_lshl_add_u32 v5, v6, 11, v5
	v_and_b32_e32 v6, 1, v7
	v_lshl_or_b32 v5, v6, 6, v5
	v_lshl_add_u32 v6, v8, 1, v5
	v_lshlrev_b32_e32 v5, 14, v2
	v_and_b32_e32 v5, 0xffff8000, v5
	v_lshl_add_u32 v3, v3, 11, v5
	v_and_b32_e32 v2, 1, v2
	v_readlane_b32 s10, v241, 52
	v_lshl_or_b32 v2, v2, 6, v3
	s_waitcnt vmcnt(6)
	v_readlane_b32 s11, v241, 53
	v_lshl_add_u32 v2, v4, 1, v2
	v_mov_b32_e32 v3, v173
	v_mov_b32_e32 v7, v173
	v_lshl_add_u64 v[142:143], s[10:11], 0, v[2:3]
	v_mov_b32_e32 v2, 0
	v_lshl_add_u64 v[140:141], s[10:11], 0, v[6:7]
	s_mov_b32 s41, -2
	s_mov_b64 s[10:11], 0
	v_add_u32_e32 v147, 0, v18
	v_mov_b32_e32 v3, v2
	v_mov_b32_e32 v4, v2
	v_mov_b32_e32 v5, v2
	v_mov_b32_e32 v6, v2
	v_mov_b32_e32 v7, v2
	v_mov_b32_e32 v8, v2
	v_mov_b32_e32 v9, v2
	v_mov_b32_e32 v18, v2
	v_mov_b32_e32 v19, v2
	v_mov_b32_e32 v20, v2
	v_mov_b32_e32 v21, v2
	v_mov_b32_e32 v22, v2
	v_mov_b32_e32 v23, v2
	v_mov_b32_e32 v24, v2
	v_mov_b32_e32 v25, v2
	v_mov_b32_e32 v34, v2
	v_mov_b32_e32 v35, v2
	v_mov_b32_e32 v36, v2
	v_mov_b32_e32 v37, v2
	v_mov_b32_e32 v38, v2
	v_mov_b32_e32 v39, v2
	v_mov_b32_e32 v40, v2
	v_mov_b32_e32 v41, v2
	v_mov_b32_e32 v50, v2
	v_mov_b32_e32 v51, v2
	v_mov_b32_e32 v52, v2
	v_mov_b32_e32 v53, v2
	v_mov_b32_e32 v54, v2
	v_mov_b32_e32 v55, v2
	v_mov_b32_e32 v56, v2
	v_mov_b32_e32 v57, v2
	v_mov_b32_e32 v10, v2
	v_mov_b32_e32 v11, v2
	v_mov_b32_e32 v12, v2
	v_mov_b32_e32 v13, v2
	v_mov_b32_e32 v14, v2
	v_mov_b32_e32 v15, v2
	v_mov_b32_e32 v16, v2
	v_mov_b32_e32 v17, v2
	v_mov_b32_e32 v26, v2
	v_mov_b32_e32 v27, v2
	v_mov_b32_e32 v28, v2
	v_mov_b32_e32 v29, v2
	v_mov_b32_e32 v30, v2
	v_mov_b32_e32 v31, v2
	v_mov_b32_e32 v32, v2
	v_mov_b32_e32 v33, v2
	v_mov_b32_e32 v42, v2
	v_mov_b32_e32 v43, v2
	v_mov_b32_e32 v44, v2
	v_mov_b32_e32 v45, v2
	v_mov_b32_e32 v46, v2
	v_mov_b32_e32 v47, v2
	v_mov_b32_e32 v48, v2
	v_mov_b32_e32 v49, v2
	v_mov_b32_e32 v58, v2
	v_mov_b32_e32 v59, v2
	v_mov_b32_e32 v60, v2
	v_mov_b32_e32 v61, v2
	v_mov_b32_e32 v62, v2
	v_mov_b32_e32 v63, v2
	v_mov_b32_e32 v64, v2
	v_mov_b32_e32 v65, v2
	v_mov_b32_e32 v66, v2
	v_mov_b32_e32 v67, v2
	v_mov_b32_e32 v68, v2
	v_mov_b32_e32 v69, v2
	v_mov_b32_e32 v70, v2
	v_mov_b32_e32 v71, v2
	v_mov_b32_e32 v72, v2
	v_mov_b32_e32 v73, v2
	v_mov_b32_e32 v82, v2
	v_mov_b32_e32 v83, v2
	v_mov_b32_e32 v84, v2
	v_mov_b32_e32 v85, v2
	v_mov_b32_e32 v86, v2
	v_mov_b32_e32 v87, v2
	v_mov_b32_e32 v88, v2
	v_mov_b32_e32 v89, v2
	v_mov_b32_e32 v102, v2
	v_mov_b32_e32 v103, v2
	v_mov_b32_e32 v104, v2
	v_mov_b32_e32 v105, v2
	v_mov_b32_e32 v106, v2
	v_mov_b32_e32 v107, v2
	v_mov_b32_e32 v108, v2
	v_mov_b32_e32 v109, v2
	v_mov_b32_e32 v118, v2
	v_mov_b32_e32 v119, v2
	v_mov_b32_e32 v120, v2
	v_mov_b32_e32 v121, v2
	v_mov_b32_e32 v122, v2
	v_mov_b32_e32 v123, v2
	v_mov_b32_e32 v124, v2
	v_mov_b32_e32 v125, v2
	v_mov_b32_e32 v74, v2
	v_mov_b32_e32 v75, v2
	v_mov_b32_e32 v76, v2
	v_mov_b32_e32 v77, v2
	v_mov_b32_e32 v78, v2
	v_mov_b32_e32 v79, v2
	v_mov_b32_e32 v80, v2
	v_mov_b32_e32 v81, v2
	v_mov_b32_e32 v90, v2
	v_mov_b32_e32 v91, v2
	v_mov_b32_e32 v92, v2
	v_mov_b32_e32 v93, v2
	v_mov_b32_e32 v94, v2
	v_mov_b32_e32 v95, v2
	v_mov_b32_e32 v96, v2
	v_mov_b32_e32 v97, v2
	v_mov_b32_e32 v110, v2
	v_mov_b32_e32 v111, v2
	v_mov_b32_e32 v112, v2
	v_mov_b32_e32 v113, v2
	v_mov_b32_e32 v114, v2
	v_mov_b32_e32 v115, v2
	v_mov_b32_e32 v116, v2
	v_mov_b32_e32 v117, v2
	v_mov_b32_e32 v126, v2
	v_mov_b32_e32 v127, v2
	v_mov_b32_e32 v128, v2
	v_mov_b32_e32 v129, v2
	v_mov_b32_e32 v130, v2
	v_mov_b32_e32 v131, v2
	v_mov_b32_e32 v132, v2
	v_mov_b32_e32 v133, v2
	v_readlane_b32 s48, v241, 50
	v_readlane_b32 s49, v241, 51
	v_readlane_b32 s50, v238, 12
	s_barrier

.LBB0_900:
	v_lshrrev_b32_e32 v22, 1, v8
	s_lshr_b32 s19, s19, 26
	v_and_b32_e32 v22, 24, v22
	v_and_b32_e32 v9, 15, v8
	s_add_i32 s19, s18, s19
	v_lshlrev_b32_e32 v23, 1, v22
	v_lshlrev_b32_e32 v8, 2, v8
	s_ashr_i32 s53, s19, 6
	v_lshl_or_b32 v144, s28, 6, v9
	v_lshl_or_b32 v9, v9, 6, v23
	s_lshl_b32 s19, s28, 13
	v_and_b32_e32 v8, 32, v8
	v_mov_b32_e32 v135, v173
	v_bitop3_b32 v23, v9, s19, v8 bitop3:0xde
	s_lshl_b32 s19, s23, 5
	v_lshl_add_u64 v[14:15], s[20:21], 0, v[172:173]
	v_lshl_add_u64 v[16:17], s[20:21], 0, v[134:135]
	s_and_b32 s20, s19, 0x60
	v_lshl_add_u64 v[10:11], s[42:43], 0, v[172:173]
	s_lshl_b32 s19, s20, 7
	v_lshl_add_u64 v[12:13], s[42:43], 0, v[134:135]
	v_mov_b32_e32 v139, v173
	v_bitop3_b32 v145, v9, s19, v8 bitop3:0xde
	s_add_i32 m0, s49, 0x18000
	v_lshl_add_u64 v[8:9], v[10:11], 0, s[84:85]
	v_lshl_add_u64 v[18:19], s[40:41], 0, v[138:139]
	v_mov_b32_e32 v137, v173
	global_load_lds_dwordx4 v[8:9], off
	v_lshl_add_u64 v[8:9], v[12:13], 0, s[84:85]
	s_add_i32 m0, s49, 0x1a000
	s_add_i32 s54, s49, 0x8000
	v_lshl_add_u64 v[20:21], s[40:41], 0, v[136:137]
	global_load_lds_dwordx4 v[8:9], off
	v_lshl_add_u64 v[8:9], v[18:19], 0, s[84:85]
	s_mov_b32 m0, s54
	s_add_i32 s55, s49, 0xa000
	global_load_lds_dwordx4 v[8:9], off
	v_lshl_add_u64 v[8:9], v[20:21], 0, s[84:85]
	s_mov_b32 m0, s55
	v_add_u32_e32 v5, v7, v5
	global_load_lds_dwordx4 v[8:9], off
	s_add_i32 m0, s49, 0x1c000
	v_lshl_add_u64 v[8:9], v[14:15], 0, s[84:85]
	global_load_lds_dwordx4 v[8:9], off
	v_lshl_add_u64 v[8:9], v[16:17], 0, s[84:85]
	s_add_i32 m0, s49, 0x1e000
	s_cmp_gt_i32 s18, 63
	global_load_lds_dwordx4 v[8:9], off
	s_waitcnt vmcnt(8)
	s_barrier
	s_waitcnt vmcnt(6)
	s_cselect_b64 s[18:19], -1, 0
	s_add_i32 s56, s53, -2
	v_add_u32_e32 v2, v4, v2
	s_cmpk_lt_u32 s22, 0x100
	v_or_b32_e32 v146, s20, v22
	v_add_lshl_u32 v6, v5, v6, 1
	v_mov_b32_e32 v7, v173
	v_add_lshl_u32 v2, v2, v3, 1
	v_mov_b32_e32 v3, v173
	v_readlane_b32 s20, v241, 8
	s_cselect_b64 s[22:23], -1, 0
	v_lshl_add_u64 v[140:141], s[0:1], 0, v[6:7]
	v_lshl_add_u64 v[142:143], s[0:1], 0, v[2:3]
	s_mov_b32 s57, 0
	v_add_u32_e32 v147, 0, v23
	v_readlane_b32 s60, v241, 37
	s_mov_b32 s61, s20
	s_barrier
	v_readlane_b32 s21, v241, 9
	s_branch .LBB0_903

.LBB0_923:
	v_lshrrev_b32_e32 v18, 1, v8
	v_and_b32_e32 v18, 24, v18
	s_lshl_b32 s11, s11, 5
	v_and_b32_e32 v9, 15, v8
	v_lshlrev_b32_e32 v19, 1, v18
	v_lshlrev_b32_e32 v8, 2, v8
	s_and_b32 s18, s11, 0x60
	v_lshl_add_u64 v[10:11], s[28:29], 0, v[172:173]
	v_mov_b32_e32 v139, v173
	v_readlane_b32 s20, v242, 50
	v_lshl_or_b32 v158, s14, 6, v9
	v_lshl_or_b32 v9, v9, 6, v19
	s_lshl_b32 s14, s14, 13
	v_and_b32_e32 v8, 32, v8
	s_lshl_b32 s11, s18, 7
	v_lshl_add_u64 v[12:13], s[28:29], 0, v[138:139]
	v_mov_b32_e32 v143, v173
	v_readlane_b32 s21, v242, 51
	v_bitop3_b32 v19, v9, s14, v8 bitop3:0xde
	v_bitop3_b32 v159, v9, s11, v8 bitop3:0xde
	s_add_i32 m0, s43, 0x18000
	v_lshl_add_u64 v[8:9], v[10:11], 0, s[84:85]
	v_lshl_add_u64 v[14:15], s[20:21], 0, v[142:143]
	v_mov_b32_e32 v141, v173
	global_load_lds_dwordx4 v[8:9], off
	v_lshl_add_u64 v[8:9], v[12:13], 0, s[84:85]
	s_add_i32 m0, s43, 0x1a000
	s_add_i32 s47, s43, 0x8000
	s_add_i32 s48, s43, 0xa000
	v_lshl_add_u64 v[16:17], s[20:21], 0, v[140:141]
	global_load_lds_dwordx4 v[8:9], off
	v_lshl_add_u64 v[8:9], v[14:15], 0, s[84:85]
	s_mov_b32 m0, s47
	s_add_u32 s14, s28, 0x40080
	global_load_lds_dwordx4 v[8:9], off
	v_lshl_add_u64 v[8:9], v[16:17], 0, s[84:85]
	s_mov_b32 m0, s48
	s_addc_u32 s15, s29, 0
	global_load_lds_dwordx4 v[8:9], off
	s_add_i32 m0, s43, 0x1c000
	v_lshl_add_u64 v[8:9], s[14:15], 0, v[172:173]
	global_load_lds_dwordx4 v[8:9], off
	v_lshl_add_u64 v[8:9], s[14:15], 0, v[138:139]
	s_add_i32 m0, s43, 0x1e000
	s_cmpk_lt_u32 s10, 0x100
	global_load_lds_dwordx4 v[8:9], off
	s_waitcnt vmcnt(8)
	s_barrier
	v_lshlrev_b32_e32 v8, 14, v6
	v_and_b32_e32 v8, 0xffff8000, v8
	v_lshl_add_u32 v5, v5, 11, v8
	v_and_b32_e32 v6, 1, v6
	v_lshl_or_b32 v5, v6, 6, v5
	v_lshl_add_u32 v144, v7, 1, v5
	v_lshlrev_b32_e32 v5, 14, v2
	v_and_b32_e32 v5, 0xffff8000, v5
	s_waitcnt vmcnt(6)
	v_lshl_add_u32 v3, v3, 11, v5
	v_and_b32_e32 v2, 1, v2
	v_lshl_or_b32 v2, v2, 6, v3
	v_readlane_b32 s14, v242, 46
	s_cselect_b64 s[10:11], -1, 0
	v_or_b32_e32 v160, s18, v18
	v_mov_b32_e32 v145, v173
	v_lshl_add_u32 v146, v4, 1, v2
	v_mov_b32_e32 v147, v173
	s_mov_b32 s49, 0
	v_add_u32_e32 v161, 0, v19
	v_readlane_b32 s50, v241, 38
	s_mov_b32 s51, s14
	s_barrier
	v_readlane_b32 s15, v242, 47
	s_branch .LBB0_926

.LBB0_937:
	v_lshrrev_b32_e32 v18, 1, v5
	v_lshl_add_u64 v[10:11], s[0:1], 0, v[172:173]
	v_mov_b32_e32 v135, v173
	v_and_b32_e32 v144, 24, v18
	s_lshl_b32 s10, s10, 5
	v_lshl_add_u64 v[12:13], s[0:1], 0, v[134:135]
	v_mov_b32_e32 v139, v173
	v_and_b32_e32 v9, 15, v5
	v_lshlrev_b32_e32 v18, 1, v144
	v_lshlrev_b32_e32 v5, 2, v5
	s_and_b32 s34, s10, 0x60
	s_add_i32 m0, s22, 0x18000
	v_lshl_add_u64 v[10:11], v[10:11], 0, s[84:85]
	v_lshl_add_u64 v[14:15], s[44:45], 0, v[138:139]
	v_mov_b32_e32 v137, v173
	v_lshl_or_b32 v145, s11, 6, v9
	v_lshl_or_b32 v9, v9, 6, v18
	s_lshl_b32 s11, s11, 13
	v_and_b32_e32 v5, 32, v5
	s_lshl_b32 s10, s34, 7
	global_load_lds_dwordx4 v[10:11], off
	v_lshl_add_u64 v[10:11], v[12:13], 0, s[84:85]
	s_add_i32 m0, s22, 0x1a000
	s_add_i32 s35, s22, 0x8000
	s_add_i32 s38, s22, 0xa000
	v_lshl_add_u64 v[16:17], s[44:45], 0, v[136:137]
	v_bitop3_b32 v146, v9, s10, v5 bitop3:0xde
	global_load_lds_dwordx4 v[10:11], off
	v_lshl_add_u64 v[10:11], v[14:15], 0, s[84:85]
	s_mov_b32 m0, s35
	s_add_u32 s10, s0, 0x40080
	v_bitop3_b32 v18, v9, s11, v5 bitop3:0xde
	global_load_lds_dwordx4 v[10:11], off
	v_lshl_add_u64 v[10:11], v[16:17], 0, s[84:85]
	s_mov_b32 m0, s38
	s_addc_u32 s11, s1, 0
	global_load_lds_dwordx4 v[10:11], off
	s_add_i32 m0, s22, 0x1c000
	v_lshl_add_u64 v[10:11], s[10:11], 0, v[172:173]
	global_load_lds_dwordx4 v[10:11], off
	v_lshl_add_u64 v[10:11], s[10:11], 0, v[134:135]
	s_add_i32 m0, s22, 0x1e000
	v_lshlrev_b32_e32 v5, 14, v7
	global_load_lds_dwordx4 v[10:11], off
	s_waitcnt vmcnt(8)
	s_barrier
	v_and_b32_e32 v5, 0xffff8000, v5
	v_lshl_add_u32 v5, v6, 11, v5
	v_and_b32_e32 v6, 1, v7
	v_lshl_or_b32 v5, v6, 6, v5
	v_lshl_add_u32 v6, v8, 1, v5
	v_lshlrev_b32_e32 v5, 14, v2
	v_and_b32_e32 v5, 0xffff8000, v5
	v_lshl_add_u32 v3, v3, 11, v5
	v_and_b32_e32 v2, 1, v2
	v_readlane_b32 s10, v241, 56
	v_lshl_or_b32 v2, v2, 6, v3
	s_waitcnt vmcnt(6)
	v_readlane_b32 s11, v241, 57
	v_lshl_add_u32 v2, v4, 1, v2
	v_mov_b32_e32 v3, v173
	v_mov_b32_e32 v7, v173
	v_lshl_add_u64 v[142:143], s[10:11], 0, v[2:3]
	v_mov_b32_e32 v2, 0
	v_lshl_add_u64 v[140:141], s[10:11], 0, v[6:7]
	s_mov_b32 s39, -2
	s_mov_b64 s[10:11], 0
	v_add_u32_e32 v147, 0, v18
	v_mov_b32_e32 v3, v2
	v_mov_b32_e32 v4, v2
	v_mov_b32_e32 v5, v2
	v_mov_b32_e32 v6, v2
	v_mov_b32_e32 v7, v2
	v_mov_b32_e32 v8, v2
	v_mov_b32_e32 v9, v2
	v_mov_b32_e32 v18, v2
	v_mov_b32_e32 v19, v2
	v_mov_b32_e32 v20, v2
	v_mov_b32_e32 v21, v2
	v_mov_b32_e32 v22, v2
	v_mov_b32_e32 v23, v2
	v_mov_b32_e32 v24, v2
	v_mov_b32_e32 v25, v2
	v_mov_b32_e32 v34, v2
	v_mov_b32_e32 v35, v2
	v_mov_b32_e32 v36, v2
	v_mov_b32_e32 v37, v2
	v_mov_b32_e32 v38, v2
	v_mov_b32_e32 v39, v2
	v_mov_b32_e32 v40, v2
	v_mov_b32_e32 v41, v2
	v_mov_b32_e32 v50, v2
	v_mov_b32_e32 v51, v2
	v_mov_b32_e32 v52, v2
	v_mov_b32_e32 v53, v2
	v_mov_b32_e32 v54, v2
	v_mov_b32_e32 v55, v2
	v_mov_b32_e32 v56, v2
	v_mov_b32_e32 v57, v2
	v_mov_b32_e32 v10, v2
	v_mov_b32_e32 v11, v2
	v_mov_b32_e32 v12, v2
	v_mov_b32_e32 v13, v2
	v_mov_b32_e32 v14, v2
	v_mov_b32_e32 v15, v2
	v_mov_b32_e32 v16, v2
	v_mov_b32_e32 v17, v2
	v_mov_b32_e32 v26, v2
	v_mov_b32_e32 v27, v2
	v_mov_b32_e32 v28, v2
	v_mov_b32_e32 v29, v2
	v_mov_b32_e32 v30, v2
	v_mov_b32_e32 v31, v2
	v_mov_b32_e32 v32, v2
	v_mov_b32_e32 v33, v2
	v_mov_b32_e32 v42, v2
	v_mov_b32_e32 v43, v2
	v_mov_b32_e32 v44, v2
	v_mov_b32_e32 v45, v2
	v_mov_b32_e32 v46, v2
	v_mov_b32_e32 v47, v2
	v_mov_b32_e32 v48, v2
	v_mov_b32_e32 v49, v2
	v_mov_b32_e32 v58, v2
	v_mov_b32_e32 v59, v2
	v_mov_b32_e32 v60, v2
	v_mov_b32_e32 v61, v2
	v_mov_b32_e32 v62, v2
	v_mov_b32_e32 v63, v2
	v_mov_b32_e32 v64, v2
	v_mov_b32_e32 v65, v2
	v_mov_b32_e32 v66, v2
	v_mov_b32_e32 v67, v2
	v_mov_b32_e32 v68, v2
	v_mov_b32_e32 v69, v2
	v_mov_b32_e32 v70, v2
	v_mov_b32_e32 v71, v2
	v_mov_b32_e32 v72, v2
	v_mov_b32_e32 v73, v2
	v_mov_b32_e32 v82, v2
	v_mov_b32_e32 v83, v2
	v_mov_b32_e32 v84, v2
	v_mov_b32_e32 v85, v2
	v_mov_b32_e32 v86, v2
	v_mov_b32_e32 v87, v2
	v_mov_b32_e32 v88, v2
	v_mov_b32_e32 v89, v2
	v_mov_b32_e32 v102, v2
	v_mov_b32_e32 v103, v2
	v_mov_b32_e32 v104, v2
	v_mov_b32_e32 v105, v2
	v_mov_b32_e32 v106, v2
	v_mov_b32_e32 v107, v2
	v_mov_b32_e32 v108, v2
	v_mov_b32_e32 v109, v2
	v_mov_b32_e32 v118, v2
	v_mov_b32_e32 v119, v2
	v_mov_b32_e32 v120, v2
	v_mov_b32_e32 v121, v2
	v_mov_b32_e32 v122, v2
	v_mov_b32_e32 v123, v2
	v_mov_b32_e32 v124, v2
	v_mov_b32_e32 v125, v2
	v_mov_b32_e32 v74, v2
	v_mov_b32_e32 v75, v2
	v_mov_b32_e32 v76, v2
	v_mov_b32_e32 v77, v2
	v_mov_b32_e32 v78, v2
	v_mov_b32_e32 v79, v2
	v_mov_b32_e32 v80, v2
	v_mov_b32_e32 v81, v2
	v_mov_b32_e32 v90, v2
	v_mov_b32_e32 v91, v2
	v_mov_b32_e32 v92, v2
	v_mov_b32_e32 v93, v2
	v_mov_b32_e32 v94, v2
	v_mov_b32_e32 v95, v2
	v_mov_b32_e32 v96, v2
	v_mov_b32_e32 v97, v2
	v_mov_b32_e32 v110, v2
	v_mov_b32_e32 v111, v2
	v_mov_b32_e32 v112, v2
	v_mov_b32_e32 v113, v2
	v_mov_b32_e32 v114, v2
	v_mov_b32_e32 v115, v2
	v_mov_b32_e32 v116, v2
	v_mov_b32_e32 v117, v2
	v_mov_b32_e32 v126, v2
	v_mov_b32_e32 v127, v2
	v_mov_b32_e32 v128, v2
	v_mov_b32_e32 v129, v2
	v_mov_b32_e32 v130, v2
	v_mov_b32_e32 v131, v2
	v_mov_b32_e32 v132, v2
	v_mov_b32_e32 v133, v2
	s_barrier

.LBB0_1003:
	v_lshrrev_b32_e32 v18, 1, v5
	v_lshl_add_u64 v[10:11], s[0:1], 0, v[172:173]
	v_mov_b32_e32 v135, v173
	v_and_b32_e32 v144, 24, v18
	s_lshl_b32 s10, s10, 5
	v_lshl_add_u64 v[12:13], s[0:1], 0, v[134:135]
	v_mov_b32_e32 v139, v173
	v_and_b32_e32 v9, 15, v5
	v_lshlrev_b32_e32 v18, 1, v144
	v_lshlrev_b32_e32 v5, 2, v5
	s_and_b32 s34, s10, 0x60
	s_add_i32 m0, s22, 0x18000
	v_lshl_add_u64 v[10:11], v[10:11], 0, s[84:85]
	v_lshl_add_u64 v[14:15], s[44:45], 0, v[138:139]
	v_mov_b32_e32 v137, v173
	v_lshl_or_b32 v145, s11, 6, v9
	v_lshl_or_b32 v9, v9, 6, v18
	s_lshl_b32 s11, s11, 13
	v_and_b32_e32 v5, 32, v5
	s_lshl_b32 s10, s34, 7
	global_load_lds_dwordx4 v[10:11], off
	v_lshl_add_u64 v[10:11], v[12:13], 0, s[84:85]
	s_add_i32 m0, s22, 0x1a000
	s_add_i32 s35, s22, 0x8000
	s_add_i32 s38, s22, 0xa000
	v_lshl_add_u64 v[16:17], s[44:45], 0, v[136:137]
	v_bitop3_b32 v146, v9, s10, v5 bitop3:0xde
	global_load_lds_dwordx4 v[10:11], off
	v_lshl_add_u64 v[10:11], v[14:15], 0, s[84:85]
	s_mov_b32 m0, s35
	s_add_u32 s10, s0, 0x40080
	v_bitop3_b32 v18, v9, s11, v5 bitop3:0xde
	global_load_lds_dwordx4 v[10:11], off
	v_lshl_add_u64 v[10:11], v[16:17], 0, s[84:85]
	s_mov_b32 m0, s38
	s_addc_u32 s11, s1, 0
	global_load_lds_dwordx4 v[10:11], off
	s_add_i32 m0, s22, 0x1c000
	v_lshl_add_u64 v[10:11], s[10:11], 0, v[172:173]
	global_load_lds_dwordx4 v[10:11], off
	v_lshl_add_u64 v[10:11], s[10:11], 0, v[134:135]
	s_add_i32 m0, s22, 0x1e000
	v_lshlrev_b32_e32 v5, 14, v7
	global_load_lds_dwordx4 v[10:11], off
	s_waitcnt vmcnt(8)
	s_barrier
	v_and_b32_e32 v5, 0xffff8000, v5
	v_lshl_add_u32 v5, v6, 11, v5
	v_and_b32_e32 v6, 1, v7
	v_lshl_or_b32 v5, v6, 6, v5
	v_lshl_add_u32 v6, v8, 1, v5
	v_lshlrev_b32_e32 v5, 14, v2
	v_and_b32_e32 v5, 0xffff8000, v5
	v_lshl_add_u32 v3, v3, 11, v5
	v_and_b32_e32 v2, 1, v2
	v_readlane_b32 s10, v241, 62
	v_lshl_or_b32 v2, v2, 6, v3
	s_waitcnt vmcnt(6)
	v_readlane_b32 s11, v241, 63
	v_lshl_add_u32 v2, v4, 1, v2
	v_mov_b32_e32 v3, v173
	v_mov_b32_e32 v7, v173
	v_lshl_add_u64 v[142:143], s[10:11], 0, v[2:3]
	v_mov_b32_e32 v2, 0
	v_lshl_add_u64 v[140:141], s[10:11], 0, v[6:7]
	s_mov_b32 s39, -2
	s_mov_b64 s[10:11], 0
	v_add_u32_e32 v147, 0, v18
	v_mov_b32_e32 v3, v2
	v_mov_b32_e32 v4, v2
	v_mov_b32_e32 v5, v2
	v_mov_b32_e32 v6, v2
	v_mov_b32_e32 v7, v2
	v_mov_b32_e32 v8, v2
	v_mov_b32_e32 v9, v2
	v_mov_b32_e32 v18, v2
	v_mov_b32_e32 v19, v2
	v_mov_b32_e32 v20, v2
	v_mov_b32_e32 v21, v2
	v_mov_b32_e32 v22, v2
	v_mov_b32_e32 v23, v2
	v_mov_b32_e32 v24, v2
	v_mov_b32_e32 v25, v2
	v_mov_b32_e32 v34, v2
	v_mov_b32_e32 v35, v2
	v_mov_b32_e32 v36, v2
	v_mov_b32_e32 v37, v2
	v_mov_b32_e32 v38, v2
	v_mov_b32_e32 v39, v2
	v_mov_b32_e32 v40, v2
	v_mov_b32_e32 v41, v2
	v_mov_b32_e32 v50, v2
	v_mov_b32_e32 v51, v2
	v_mov_b32_e32 v52, v2
	v_mov_b32_e32 v53, v2
	v_mov_b32_e32 v54, v2
	v_mov_b32_e32 v55, v2
	v_mov_b32_e32 v56, v2
	v_mov_b32_e32 v57, v2
	v_mov_b32_e32 v10, v2
	v_mov_b32_e32 v11, v2
	v_mov_b32_e32 v12, v2
	v_mov_b32_e32 v13, v2
	v_mov_b32_e32 v14, v2
	v_mov_b32_e32 v15, v2
	v_mov_b32_e32 v16, v2
	v_mov_b32_e32 v17, v2
	v_mov_b32_e32 v26, v2
	v_mov_b32_e32 v27, v2
	v_mov_b32_e32 v28, v2
	v_mov_b32_e32 v29, v2
	v_mov_b32_e32 v30, v2
	v_mov_b32_e32 v31, v2
	v_mov_b32_e32 v32, v2
	v_mov_b32_e32 v33, v2
	v_mov_b32_e32 v42, v2
	v_mov_b32_e32 v43, v2
	v_mov_b32_e32 v44, v2
	v_mov_b32_e32 v45, v2
	v_mov_b32_e32 v46, v2
	v_mov_b32_e32 v47, v2
	v_mov_b32_e32 v48, v2
	v_mov_b32_e32 v49, v2
	v_mov_b32_e32 v58, v2
	v_mov_b32_e32 v59, v2
	v_mov_b32_e32 v60, v2
	v_mov_b32_e32 v61, v2
	v_mov_b32_e32 v62, v2
	v_mov_b32_e32 v63, v2
	v_mov_b32_e32 v64, v2
	v_mov_b32_e32 v65, v2
	v_mov_b32_e32 v66, v2
	v_mov_b32_e32 v67, v2
	v_mov_b32_e32 v68, v2
	v_mov_b32_e32 v69, v2
	v_mov_b32_e32 v70, v2
	v_mov_b32_e32 v71, v2
	v_mov_b32_e32 v72, v2
	v_mov_b32_e32 v73, v2
	v_mov_b32_e32 v82, v2
	v_mov_b32_e32 v83, v2
	v_mov_b32_e32 v84, v2
	v_mov_b32_e32 v85, v2
	v_mov_b32_e32 v86, v2
	v_mov_b32_e32 v87, v2
	v_mov_b32_e32 v88, v2
	v_mov_b32_e32 v89, v2
	v_mov_b32_e32 v102, v2
	v_mov_b32_e32 v103, v2
	v_mov_b32_e32 v104, v2
	v_mov_b32_e32 v105, v2
	v_mov_b32_e32 v106, v2
	v_mov_b32_e32 v107, v2
	v_mov_b32_e32 v108, v2
	v_mov_b32_e32 v109, v2
	v_mov_b32_e32 v110, v2
	v_mov_b32_e32 v111, v2
	v_mov_b32_e32 v112, v2
	v_mov_b32_e32 v113, v2
	v_mov_b32_e32 v118, v2
	v_mov_b32_e32 v119, v2
	v_mov_b32_e32 v120, v2
	v_mov_b32_e32 v121, v2
	v_mov_b32_e32 v74, v2
	v_mov_b32_e32 v75, v2
	v_mov_b32_e32 v76, v2
	v_mov_b32_e32 v77, v2
	v_mov_b32_e32 v78, v2
	v_mov_b32_e32 v79, v2
	v_mov_b32_e32 v80, v2
	v_mov_b32_e32 v81, v2
	v_mov_b32_e32 v90, v2
	v_mov_b32_e32 v91, v2
	v_mov_b32_e32 v92, v2
	v_mov_b32_e32 v93, v2
	v_mov_b32_e32 v94, v2
	v_mov_b32_e32 v95, v2
	v_mov_b32_e32 v96, v2
	v_mov_b32_e32 v97, v2
	v_mov_b32_e32 v114, v2
	v_mov_b32_e32 v115, v2
	v_mov_b32_e32 v116, v2
	v_mov_b32_e32 v117, v2
	v_mov_b32_e32 v122, v2
	v_mov_b32_e32 v123, v2
	v_mov_b32_e32 v124, v2
	v_mov_b32_e32 v125, v2
	v_mov_b32_e32 v126, v2
	v_mov_b32_e32 v127, v2
	v_mov_b32_e32 v128, v2
	v_mov_b32_e32 v129, v2
	v_mov_b32_e32 v130, v2
	v_mov_b32_e32 v131, v2
	v_mov_b32_e32 v132, v2
	v_mov_b32_e32 v133, v2
	v_readlane_b32 s46, v241, 60
	v_readlane_b32 s47, v241, 61
	v_readlane_b32 s48, v240, 1
	v_readlane_b32 s49, v240, 2
	s_barrier

.LBB0_1011:
	v_lshrrev_b32_e32 v18, 1, v8
	v_and_b32_e32 v18, 24, v18
	s_lshl_b32 s11, s11, 5
	v_and_b32_e32 v9, 15, v8
	v_lshlrev_b32_e32 v19, 1, v18
	v_lshlrev_b32_e32 v8, 2, v8
	s_and_b32 s18, s11, 0x60
	v_lshl_add_u64 v[10:11], s[28:29], 0, v[172:173]
	v_mov_b32_e32 v179, v173
	v_readlane_b32 s22, v241, 16
	v_lshl_or_b32 v204, s14, 6, v9
	v_lshl_or_b32 v9, v9, 6, v19
	s_lshl_b32 s14, s14, 13
	v_and_b32_e32 v8, 32, v8
	s_lshl_b32 s11, s18, 7
	v_lshl_add_u64 v[12:13], s[28:29], 0, v[178:179]
	v_mov_b32_e32 v183, v173
	v_readlane_b32 s23, v241, 17
	v_bitop3_b32 v19, v9, s14, v8 bitop3:0xde
	v_bitop3_b32 v205, v9, s11, v8 bitop3:0xde
	s_add_i32 m0, s43, 0x18000
	v_lshl_add_u64 v[8:9], v[10:11], 0, s[84:85]
	v_lshl_add_u64 v[14:15], s[22:23], 0, v[182:183]
	v_mov_b32_e32 v181, v173
	global_load_lds_dwordx4 v[8:9], off
	v_lshl_add_u64 v[8:9], v[12:13], 0, s[84:85]
	s_add_i32 m0, s43, 0x1a000
	s_add_i32 s47, s43, 0x8000
	s_add_i32 s48, s43, 0xa000
	v_lshl_add_u64 v[16:17], s[22:23], 0, v[180:181]
	global_load_lds_dwordx4 v[8:9], off
	v_lshl_add_u64 v[8:9], v[14:15], 0, s[84:85]
	s_mov_b32 m0, s47
	s_add_u32 s14, s28, 0x40080
	global_load_lds_dwordx4 v[8:9], off
	v_lshl_add_u64 v[8:9], v[16:17], 0, s[84:85]
	s_mov_b32 m0, s48
	s_addc_u32 s15, s29, 0
	global_load_lds_dwordx4 v[8:9], off
	s_add_i32 m0, s43, 0x1c000
	v_lshl_add_u64 v[8:9], s[14:15], 0, v[172:173]
	global_load_lds_dwordx4 v[8:9], off
	v_lshl_add_u64 v[8:9], s[14:15], 0, v[178:179]
	s_add_i32 m0, s43, 0x1e000
	s_cmpk_lt_u32 s10, 0x100
	global_load_lds_dwordx4 v[8:9], off
	s_waitcnt vmcnt(8)
	s_barrier
	v_lshlrev_b32_e32 v8, 14, v6
	v_and_b32_e32 v8, 0xffff8000, v8
	v_lshl_add_u32 v5, v5, 11, v8
	v_and_b32_e32 v6, 1, v6
	v_lshl_or_b32 v5, v6, 6, v5
	v_lshl_add_u32 v184, v7, 1, v5
	v_lshlrev_b32_e32 v5, 14, v2
	v_and_b32_e32 v5, 0xffff8000, v5
	s_waitcnt vmcnt(6)
	v_lshl_add_u32 v3, v3, 11, v5
	v_and_b32_e32 v2, 1, v2
	v_lshl_or_b32 v2, v2, 6, v3
	v_readlane_b32 s14, v241, 8
	s_cselect_b64 s[10:11], -1, 0
	v_or_b32_e32 v206, s18, v18
	v_mov_b32_e32 v185, v173
	v_lshl_add_u32 v186, v4, 1, v2
	v_mov_b32_e32 v187, v173
	s_mov_b64 s[20:21], -1
	v_add_u32_e32 v207, 0, v19
	v_readlane_b32 s49, v241, 37
	s_mov_b32 s50, s14
	s_mov_b64 s[18:19], s[22:23]
	s_barrier
	v_readlane_b32 s15, v241, 9
	s_branch .LBB0_1014

.LBB0_1094:
	v_lshrrev_b32_e32 v18, 1, v11
	v_and_b32_e32 v145, 24, v18
	v_and_b32_e32 v17, 15, v11
	v_lshlrev_b32_e32 v18, 1, v145
	v_lshlrev_b32_e32 v11, 2, v11
	v_lshl_or_b32 v144, s28, 6, v17
	v_lshl_or_b32 v17, v17, 6, v18
	s_lshl_b32 s28, s28, 13
	v_and_b32_e32 v11, 32, v11
	v_bitop3_b32 v18, v17, s28, v11 bitop3:0xde
	s_lshl_b32 s28, s29, 5
	s_and_b32 s39, s28, 0x60
	s_add_i32 m0, s1, 0x18000
	v_lshl_add_u64 v[8:9], v[8:9], 0, s[84:85]
	s_lshl_b32 s28, s39, 7
	global_load_lds_dwordx4 v[8:9], off
	v_lshl_add_u64 v[6:7], v[6:7], 0, s[84:85]
	s_add_i32 m0, s1, 0x1a000
	s_add_i32 s40, s1, 0x8000
	s_add_i32 s41, s1, 0xa000
	v_bitop3_b32 v146, v17, s28, v11 bitop3:0xde
	global_load_lds_dwordx4 v[6:7], off
	v_lshl_add_u64 v[4:5], v[4:5], 0, s[84:85]
	s_mov_b32 m0, s40
	s_add_u32 s28, s10, 0x80080
	global_load_lds_dwordx4 v[4:5], off
	v_lshl_add_u64 v[2:3], v[2:3], 0, s[84:85]
	s_mov_b32 m0, s41
	s_addc_u32 s29, s11, 0
	global_load_lds_dwordx4 v[2:3], off
	s_add_i32 m0, s1, 0x1c000
	v_lshl_add_u64 v[2:3], s[28:29], 0, v[172:173]
	global_load_lds_dwordx4 v[2:3], off
	v_lshl_add_u64 v[2:3], s[28:29], 0, v[138:139]
	s_add_i32 m0, s1, 0x1e000
	s_add_u32 s42, s78, s22
	global_load_lds_dwordx4 v[2:3], off
	s_waitcnt vmcnt(8)
	s_barrier
	v_lshlrev_b32_e32 v2, 15, v10
	v_and_b32_e32 v2, 0xffff0000, v2
	s_addc_u32 s43, s79, s23
	v_lshl_add_u32 v2, v12, 12, v2
	v_and_b32_e32 v3, 1, v10
	v_readlane_b32 s28, v240, 3
	v_lshl_or_b32 v2, v3, 6, v2
	s_add_u32 s22, s28, s22
	v_readlane_b32 s28, v240, 4
	v_lshl_add_u32 v2, v13, 1, v2
	v_mov_b32_e32 v3, v173
	s_addc_u32 s23, s28, s23
	v_lshl_add_u64 v[140:141], s[22:23], 0, v[2:3]
	v_lshlrev_b32_e32 v2, 15, v14
	v_and_b32_e32 v2, 0xffff0000, v2
	v_lshl_add_u32 v2, v15, 12, v2
	v_and_b32_e32 v3, 1, v14
	v_lshl_or_b32 v2, v3, 6, v2
	v_lshl_add_u32 v2, v16, 1, v2
	v_mov_b32_e32 v3, v173
	s_waitcnt vmcnt(6)
	v_lshl_add_u64 v[142:143], s[22:23], 0, v[2:3]
	v_readlane_b32 s22, v240, 5
	s_add_u32 s44, s22, s18
	v_readlane_b32 s18, v240, 6
	v_mov_b32_e32 v2, 0
	s_addc_u32 s45, s18, s19
	s_mov_b32 s46, -2
	s_mov_b64 s[18:19], 0
	v_add_u32_e32 v147, 0, v18
	v_mov_b32_e32 v3, v2
	v_mov_b32_e32 v4, v2
	v_mov_b32_e32 v5, v2
	v_mov_b32_e32 v6, v2
	v_mov_b32_e32 v7, v2
	v_mov_b32_e32 v8, v2
	v_mov_b32_e32 v9, v2
	v_mov_b32_e32 v18, v2
	v_mov_b32_e32 v19, v2
	v_mov_b32_e32 v20, v2
	v_mov_b32_e32 v21, v2
	v_mov_b32_e32 v22, v2
	v_mov_b32_e32 v23, v2
	v_mov_b32_e32 v24, v2
	v_mov_b32_e32 v25, v2
	v_mov_b32_e32 v34, v2
	v_mov_b32_e32 v35, v2
	v_mov_b32_e32 v36, v2
	v_mov_b32_e32 v37, v2
	v_mov_b32_e32 v38, v2
	v_mov_b32_e32 v39, v2
	v_mov_b32_e32 v40, v2
	v_mov_b32_e32 v41, v2
	v_mov_b32_e32 v50, v2
	v_mov_b32_e32 v51, v2
	v_mov_b32_e32 v52, v2
	v_mov_b32_e32 v53, v2
	v_mov_b32_e32 v54, v2
	v_mov_b32_e32 v55, v2
	v_mov_b32_e32 v56, v2
	v_mov_b32_e32 v57, v2
	v_mov_b32_e32 v10, v2
	v_mov_b32_e32 v11, v2
	v_mov_b32_e32 v12, v2
	v_mov_b32_e32 v13, v2
	v_mov_b32_e32 v14, v2
	v_mov_b32_e32 v15, v2
	v_mov_b32_e32 v16, v2
	v_mov_b32_e32 v17, v2
	v_mov_b32_e32 v26, v2
	v_mov_b32_e32 v27, v2
	v_mov_b32_e32 v28, v2
	v_mov_b32_e32 v29, v2
	v_mov_b32_e32 v30, v2
	v_mov_b32_e32 v31, v2
	v_mov_b32_e32 v32, v2
	v_mov_b32_e32 v33, v2
	v_mov_b32_e32 v42, v2
	v_mov_b32_e32 v43, v2
	v_mov_b32_e32 v44, v2
	v_mov_b32_e32 v45, v2
	v_mov_b32_e32 v46, v2
	v_mov_b32_e32 v47, v2
	v_mov_b32_e32 v48, v2
	v_mov_b32_e32 v49, v2
	v_mov_b32_e32 v58, v2
	v_mov_b32_e32 v59, v2
	v_mov_b32_e32 v60, v2
	v_mov_b32_e32 v61, v2
	v_mov_b32_e32 v62, v2
	v_mov_b32_e32 v63, v2
	v_mov_b32_e32 v64, v2
	v_mov_b32_e32 v65, v2
	v_mov_b32_e32 v66, v2
	v_mov_b32_e32 v67, v2
	v_mov_b32_e32 v68, v2
	v_mov_b32_e32 v69, v2
	v_mov_b32_e32 v70, v2
	v_mov_b32_e32 v71, v2
	v_mov_b32_e32 v72, v2
	v_mov_b32_e32 v73, v2
	v_mov_b32_e32 v82, v2
	v_mov_b32_e32 v83, v2
	v_mov_b32_e32 v84, v2
	v_mov_b32_e32 v85, v2
	v_mov_b32_e32 v86, v2
	v_mov_b32_e32 v87, v2
	v_mov_b32_e32 v88, v2
	v_mov_b32_e32 v89, v2
	v_mov_b32_e32 v102, v2
	v_mov_b32_e32 v103, v2
	v_mov_b32_e32 v104, v2
	v_mov_b32_e32 v105, v2
	v_mov_b32_e32 v106, v2
	v_mov_b32_e32 v107, v2
	v_mov_b32_e32 v108, v2
	v_mov_b32_e32 v109, v2
	v_mov_b32_e32 v110, v2
	v_mov_b32_e32 v111, v2
	v_mov_b32_e32 v112, v2
	v_mov_b32_e32 v113, v2
	v_mov_b32_e32 v114, v2
	v_mov_b32_e32 v115, v2
	v_mov_b32_e32 v116, v2
	v_mov_b32_e32 v117, v2
	v_mov_b32_e32 v74, v2
	v_mov_b32_e32 v75, v2
	v_mov_b32_e32 v76, v2
	v_mov_b32_e32 v77, v2
	v_mov_b32_e32 v78, v2
	v_mov_b32_e32 v79, v2
	v_mov_b32_e32 v80, v2
	v_mov_b32_e32 v81, v2
	v_mov_b32_e32 v90, v2
	v_mov_b32_e32 v91, v2
	v_mov_b32_e32 v92, v2
	v_mov_b32_e32 v93, v2
	v_mov_b32_e32 v94, v2
	v_mov_b32_e32 v95, v2
	v_mov_b32_e32 v96, v2
	v_mov_b32_e32 v97, v2
	v_mov_b32_e32 v118, v2
	v_mov_b32_e32 v119, v2
	v_mov_b32_e32 v120, v2
	v_mov_b32_e32 v121, v2
	v_mov_b32_e32 v122, v2
	v_mov_b32_e32 v123, v2
	v_mov_b32_e32 v124, v2
	v_mov_b32_e32 v125, v2
	v_mov_b32_e32 v126, v2
	v_mov_b32_e32 v127, v2
	v_mov_b32_e32 v128, v2
	v_mov_b32_e32 v129, v2
	v_mov_b32_e32 v130, v2
	v_mov_b32_e32 v131, v2
	v_mov_b32_e32 v132, v2
	v_mov_b32_e32 v133, v2
	s_barrier

.LBB0_1159:
	v_lshrrev_b32_e32 v18, 1, v6
	v_and_b32_e32 v145, 24, v18
	v_and_b32_e32 v9, 15, v6
	v_lshlrev_b32_e32 v18, 1, v145
	v_lshlrev_b32_e32 v6, 2, v6
	v_lshl_or_b32 v144, s10, 6, v9
	v_lshl_or_b32 v9, v9, 6, v18
	s_lshl_b32 s10, s10, 13
	v_and_b32_e32 v6, 32, v6
	v_lshl_add_u64 v[10:11], s[0:1], 0, v[172:173]
	v_mov_b32_e32 v139, v173
	v_bitop3_b32 v18, v9, s10, v6 bitop3:0xde
	s_lshl_b32 s10, s11, 5
	v_lshl_add_u64 v[12:13], s[0:1], 0, v[138:139]
	v_mov_b32_e32 v135, v173
	s_and_b32 s34, s10, 0x60
	s_add_i32 m0, s22, 0x18000
	v_lshl_add_u64 v[10:11], v[10:11], 0, s[84:85]
	v_lshl_add_u64 v[14:15], s[44:45], 0, v[134:135]
	v_mov_b32_e32 v137, v173
	s_lshl_b32 s10, s34, 7
	global_load_lds_dwordx4 v[10:11], off
	v_lshl_add_u64 v[10:11], v[12:13], 0, s[84:85]
	s_add_i32 m0, s22, 0x1a000
	s_add_i32 s35, s22, 0x8000
	s_add_i32 s38, s22, 0xa000
	v_lshl_add_u64 v[16:17], s[44:45], 0, v[136:137]
	v_bitop3_b32 v146, v9, s10, v6 bitop3:0xde
	global_load_lds_dwordx4 v[10:11], off
	v_lshl_add_u64 v[10:11], v[14:15], 0, s[84:85]
	s_mov_b32 m0, s35
	s_add_u32 s10, s0, 0x80080
	global_load_lds_dwordx4 v[10:11], off
	v_lshl_add_u64 v[10:11], v[16:17], 0, s[84:85]
	s_mov_b32 m0, s38
	s_addc_u32 s11, s1, 0
	global_load_lds_dwordx4 v[10:11], off
	s_add_i32 m0, s22, 0x1c000
	v_lshl_add_u64 v[10:11], s[10:11], 0, v[172:173]
	global_load_lds_dwordx4 v[10:11], off
	v_lshl_add_u64 v[10:11], s[10:11], 0, v[138:139]
	s_add_i32 m0, s22, 0x1e000
	v_lshlrev_b32_e32 v6, 15, v2
	global_load_lds_dwordx4 v[10:11], off
	s_waitcnt vmcnt(8)
	s_barrier
	v_and_b32_e32 v6, 0xffff0000, v6
	v_lshl_add_u32 v3, v3, 12, v6
	v_and_b32_e32 v2, 1, v2
	v_lshl_or_b32 v2, v2, 6, v3
	v_readlane_b32 s10, v240, 9
	v_lshl_add_u32 v2, v4, 1, v2
	v_mov_b32_e32 v3, v173
	v_readlane_b32 s11, v240, 10
	s_waitcnt vmcnt(6)
	s_mov_b32 s39, -2
	v_add_u32_e32 v147, 0, v18
	v_lshl_add_u64 v[140:141], s[10:11], 0, v[2:3]
	v_lshlrev_b32_e32 v2, 15, v5
	v_and_b32_e32 v2, 0xffff0000, v2
	v_lshl_add_u32 v2, v7, 12, v2
	v_and_b32_e32 v3, 1, v5
	v_lshl_or_b32 v2, v3, 6, v2
	v_lshl_add_u32 v2, v8, 1, v2
	v_mov_b32_e32 v3, v173
	v_lshl_add_u64 v[142:143], s[10:11], 0, v[2:3]
	v_mov_b32_e32 v2, 0
	s_mov_b64 s[10:11], 0
	v_mov_b32_e32 v3, v2
	v_mov_b32_e32 v4, v2
	v_mov_b32_e32 v5, v2
	v_mov_b32_e32 v6, v2
	v_mov_b32_e32 v7, v2
	v_mov_b32_e32 v8, v2
	v_mov_b32_e32 v9, v2
	v_mov_b32_e32 v18, v2
	v_mov_b32_e32 v19, v2
	v_mov_b32_e32 v20, v2
	v_mov_b32_e32 v21, v2
	v_mov_b32_e32 v22, v2
	v_mov_b32_e32 v23, v2
	v_mov_b32_e32 v24, v2
	v_mov_b32_e32 v25, v2
	v_mov_b32_e32 v34, v2
	v_mov_b32_e32 v35, v2
	v_mov_b32_e32 v36, v2
	v_mov_b32_e32 v37, v2
	v_mov_b32_e32 v38, v2
	v_mov_b32_e32 v39, v2
	v_mov_b32_e32 v40, v2
	v_mov_b32_e32 v41, v2
	v_mov_b32_e32 v50, v2
	v_mov_b32_e32 v51, v2
	v_mov_b32_e32 v52, v2
	v_mov_b32_e32 v53, v2
	v_mov_b32_e32 v54, v2
	v_mov_b32_e32 v55, v2
	v_mov_b32_e32 v56, v2
	v_mov_b32_e32 v57, v2
	v_mov_b32_e32 v10, v2
	v_mov_b32_e32 v11, v2
	v_mov_b32_e32 v12, v2
	v_mov_b32_e32 v13, v2
	v_mov_b32_e32 v14, v2
	v_mov_b32_e32 v15, v2
	v_mov_b32_e32 v16, v2
	v_mov_b32_e32 v17, v2
	v_mov_b32_e32 v26, v2
	v_mov_b32_e32 v27, v2
	v_mov_b32_e32 v28, v2
	v_mov_b32_e32 v29, v2
	v_mov_b32_e32 v30, v2
	v_mov_b32_e32 v31, v2
	v_mov_b32_e32 v32, v2
	v_mov_b32_e32 v33, v2
	v_mov_b32_e32 v42, v2
	v_mov_b32_e32 v43, v2
	v_mov_b32_e32 v44, v2
	v_mov_b32_e32 v45, v2
	v_mov_b32_e32 v46, v2
	v_mov_b32_e32 v47, v2
	v_mov_b32_e32 v48, v2
	v_mov_b32_e32 v49, v2
	v_mov_b32_e32 v58, v2
	v_mov_b32_e32 v59, v2
	v_mov_b32_e32 v60, v2
	v_mov_b32_e32 v61, v2
	v_mov_b32_e32 v62, v2
	v_mov_b32_e32 v63, v2
	v_mov_b32_e32 v64, v2
	v_mov_b32_e32 v65, v2
	v_mov_b32_e32 v66, v2
	v_mov_b32_e32 v67, v2
	v_mov_b32_e32 v68, v2
	v_mov_b32_e32 v69, v2
	v_mov_b32_e32 v70, v2
	v_mov_b32_e32 v71, v2
	v_mov_b32_e32 v72, v2
	v_mov_b32_e32 v73, v2
	v_mov_b32_e32 v82, v2
	v_mov_b32_e32 v83, v2
	v_mov_b32_e32 v84, v2
	v_mov_b32_e32 v85, v2
	v_mov_b32_e32 v86, v2
	v_mov_b32_e32 v87, v2
	v_mov_b32_e32 v88, v2
	v_mov_b32_e32 v89, v2
	v_mov_b32_e32 v102, v2
	v_mov_b32_e32 v103, v2
	v_mov_b32_e32 v104, v2
	v_mov_b32_e32 v105, v2
	v_mov_b32_e32 v106, v2
	v_mov_b32_e32 v107, v2
	v_mov_b32_e32 v108, v2
	v_mov_b32_e32 v109, v2
	v_mov_b32_e32 v110, v2
	v_mov_b32_e32 v111, v2
	v_mov_b32_e32 v112, v2
	v_mov_b32_e32 v113, v2
	v_mov_b32_e32 v114, v2
	v_mov_b32_e32 v115, v2
	v_mov_b32_e32 v116, v2
	v_mov_b32_e32 v117, v2
	v_mov_b32_e32 v74, v2
	v_mov_b32_e32 v75, v2
	v_mov_b32_e32 v76, v2
	v_mov_b32_e32 v77, v2
	v_mov_b32_e32 v78, v2
	v_mov_b32_e32 v79, v2
	v_mov_b32_e32 v80, v2
	v_mov_b32_e32 v81, v2
	v_mov_b32_e32 v90, v2
	v_mov_b32_e32 v91, v2
	v_mov_b32_e32 v92, v2
	v_mov_b32_e32 v93, v2
	v_mov_b32_e32 v94, v2
	v_mov_b32_e32 v95, v2
	v_mov_b32_e32 v96, v2
	v_mov_b32_e32 v97, v2
	v_mov_b32_e32 v118, v2
	v_mov_b32_e32 v119, v2
	v_mov_b32_e32 v120, v2
	v_mov_b32_e32 v121, v2
	v_mov_b32_e32 v122, v2
	v_mov_b32_e32 v123, v2
	v_mov_b32_e32 v124, v2
	v_mov_b32_e32 v125, v2
	v_mov_b32_e32 v126, v2
	v_mov_b32_e32 v127, v2
	v_mov_b32_e32 v128, v2
	v_mov_b32_e32 v129, v2
	v_mov_b32_e32 v130, v2
	v_mov_b32_e32 v131, v2
	v_mov_b32_e32 v132, v2
	v_mov_b32_e32 v133, v2
	v_readlane_b32 s46, v240, 7
	v_readlane_b32 s47, v240, 8
	v_readlane_b32 s48, v240, 12
	v_readlane_b32 s49, v240, 13
	s_barrier

.LBB0_1168:
	v_lshrrev_b32_e32 v18, 1, v5
	v_lshl_add_u64 v[10:11], s[0:1], 0, v[172:173]
	v_mov_b32_e32 v131, v173
	v_and_b32_e32 v145, 24, v18
	s_lshl_b32 s10, s10, 5
	v_lshl_add_u64 v[12:13], s[0:1], 0, v[130:131]
	v_mov_b32_e32 v135, v173
	v_and_b32_e32 v9, 15, v5
	v_lshlrev_b32_e32 v18, 1, v145
	v_lshlrev_b32_e32 v5, 2, v5
	s_and_b32 s34, s10, 0x60
	s_add_i32 m0, s22, 0x18000
	v_lshl_add_u64 v[10:11], v[10:11], 0, s[84:85]
	v_lshl_add_u64 v[14:15], s[44:45], 0, v[134:135]
	v_mov_b32_e32 v133, v173
	v_lshl_or_b32 v144, s11, 6, v9
	v_lshl_or_b32 v9, v9, 6, v18
	s_lshl_b32 s11, s11, 13
	v_and_b32_e32 v5, 32, v5
	s_lshl_b32 s10, s34, 7
	global_load_lds_dwordx4 v[10:11], off
	v_lshl_add_u64 v[10:11], v[12:13], 0, s[84:85]
	s_add_i32 m0, s22, 0x1a000
	s_add_i32 s35, s22, 0x8000
	s_add_i32 s38, s22, 0xa000
	v_lshl_add_u64 v[16:17], s[44:45], 0, v[132:133]
	v_bitop3_b32 v146, v9, s10, v5 bitop3:0xde
	global_load_lds_dwordx4 v[10:11], off
	v_lshl_add_u64 v[10:11], v[14:15], 0, s[84:85]
	s_mov_b32 m0, s35
	s_add_u32 s10, s0, 0x80080
	v_bitop3_b32 v18, v9, s11, v5 bitop3:0xde
	global_load_lds_dwordx4 v[10:11], off
	v_lshl_add_u64 v[10:11], v[16:17], 0, s[84:85]
	s_mov_b32 m0, s38
	s_addc_u32 s11, s1, 0
	global_load_lds_dwordx4 v[10:11], off
	s_add_i32 m0, s22, 0x1c000
	v_lshl_add_u64 v[10:11], s[10:11], 0, v[172:173]
	global_load_lds_dwordx4 v[10:11], off
	v_lshl_add_u64 v[10:11], s[10:11], 0, v[130:131]
	s_add_i32 m0, s22, 0x1e000
	v_lshlrev_b32_e32 v5, 15, v7
	global_load_lds_dwordx4 v[10:11], off
	s_waitcnt vmcnt(8)
	s_barrier
	v_and_b32_e32 v5, 0xffff0000, v5
	v_lshl_add_u32 v5, v6, 12, v5
	v_and_b32_e32 v6, 1, v7
	v_lshl_or_b32 v5, v6, 6, v5
	v_lshl_add_u32 v6, v8, 1, v5
	v_lshlrev_b32_e32 v5, 15, v2
	v_and_b32_e32 v5, 0xffff0000, v5
	v_lshl_add_u32 v3, v3, 12, v5
	v_and_b32_e32 v2, 1, v2
	v_readlane_b32 s10, v240, 16
	v_lshl_or_b32 v2, v2, 6, v3
	s_waitcnt vmcnt(6)
	v_readlane_b32 s11, v240, 17
	v_lshl_add_u32 v2, v4, 1, v2
	v_mov_b32_e32 v3, v173
	v_mov_b32_e32 v7, v173
	v_lshl_add_u64 v[142:143], s[10:11], 0, v[2:3]
	v_mov_b32_e32 v2, 0
	v_lshl_add_u64 v[136:137], s[10:11], 0, v[6:7]
	s_mov_b32 s39, -2
	s_mov_b64 s[10:11], 0
	v_add_u32_e32 v147, 0, v18
	v_mov_b32_e32 v3, v2
	v_mov_b32_e32 v4, v2
	v_mov_b32_e32 v5, v2
	v_mov_b32_e32 v6, v2
	v_mov_b32_e32 v7, v2
	v_mov_b32_e32 v8, v2
	v_mov_b32_e32 v9, v2
	v_mov_b32_e32 v18, v2
	v_mov_b32_e32 v19, v2
	v_mov_b32_e32 v20, v2
	v_mov_b32_e32 v21, v2
	v_mov_b32_e32 v22, v2
	v_mov_b32_e32 v23, v2
	v_mov_b32_e32 v24, v2
	v_mov_b32_e32 v25, v2
	v_mov_b32_e32 v34, v2
	v_mov_b32_e32 v35, v2
	v_mov_b32_e32 v36, v2
	v_mov_b32_e32 v37, v2
	v_mov_b32_e32 v38, v2
	v_mov_b32_e32 v39, v2
	v_mov_b32_e32 v40, v2
	v_mov_b32_e32 v41, v2
	v_mov_b32_e32 v50, v2
	v_mov_b32_e32 v51, v2
	v_mov_b32_e32 v52, v2
	v_mov_b32_e32 v53, v2
	v_mov_b32_e32 v54, v2
	v_mov_b32_e32 v55, v2
	v_mov_b32_e32 v56, v2
	v_mov_b32_e32 v57, v2
	v_mov_b32_e32 v10, v2
	v_mov_b32_e32 v11, v2
	v_mov_b32_e32 v12, v2
	v_mov_b32_e32 v13, v2
	v_mov_b32_e32 v14, v2
	v_mov_b32_e32 v15, v2
	v_mov_b32_e32 v16, v2
	v_mov_b32_e32 v17, v2
	v_mov_b32_e32 v26, v2
	v_mov_b32_e32 v27, v2
	v_mov_b32_e32 v28, v2
	v_mov_b32_e32 v29, v2
	v_mov_b32_e32 v30, v2
	v_mov_b32_e32 v31, v2
	v_mov_b32_e32 v32, v2
	v_mov_b32_e32 v33, v2
	v_mov_b32_e32 v42, v2
	v_mov_b32_e32 v43, v2
	v_mov_b32_e32 v44, v2
	v_mov_b32_e32 v45, v2
	v_mov_b32_e32 v46, v2
	v_mov_b32_e32 v47, v2
	v_mov_b32_e32 v48, v2
	v_mov_b32_e32 v49, v2
	v_mov_b32_e32 v58, v2
	v_mov_b32_e32 v59, v2
	v_mov_b32_e32 v60, v2
	v_mov_b32_e32 v61, v2
	v_mov_b32_e32 v62, v2
	v_mov_b32_e32 v63, v2
	v_mov_b32_e32 v64, v2
	v_mov_b32_e32 v65, v2
	v_mov_b32_e32 v66, v2
	v_mov_b32_e32 v67, v2
	v_mov_b32_e32 v68, v2
	v_mov_b32_e32 v69, v2
	v_mov_b32_e32 v70, v2
	v_mov_b32_e32 v71, v2
	v_mov_b32_e32 v72, v2
	v_mov_b32_e32 v73, v2
	v_mov_b32_e32 v82, v2
	v_mov_b32_e32 v83, v2
	v_mov_b32_e32 v84, v2
	v_mov_b32_e32 v85, v2
	v_mov_b32_e32 v86, v2
	v_mov_b32_e32 v87, v2
	v_mov_b32_e32 v88, v2
	v_mov_b32_e32 v89, v2
	v_mov_b32_e32 v102, v2
	v_mov_b32_e32 v103, v2
	v_mov_b32_e32 v104, v2
	v_mov_b32_e32 v105, v2
	v_mov_b32_e32 v106, v2
	v_mov_b32_e32 v107, v2
	v_mov_b32_e32 v108, v2
	v_mov_b32_e32 v109, v2
	v_mov_b32_e32 v118, v2
	v_mov_b32_e32 v119, v2
	v_mov_b32_e32 v120, v2
	v_mov_b32_e32 v121, v2
	v_mov_b32_e32 v122, v2
	v_mov_b32_e32 v123, v2
	v_mov_b32_e32 v124, v2
	v_mov_b32_e32 v125, v2
	v_mov_b32_e32 v74, v2
	v_mov_b32_e32 v75, v2
	v_mov_b32_e32 v76, v2
	v_mov_b32_e32 v77, v2
	v_mov_b32_e32 v78, v2
	v_mov_b32_e32 v79, v2
	v_mov_b32_e32 v80, v2
	v_mov_b32_e32 v81, v2
	v_mov_b32_e32 v90, v2
	v_mov_b32_e32 v91, v2
	v_mov_b32_e32 v92, v2
	v_mov_b32_e32 v93, v2
	v_mov_b32_e32 v94, v2
	v_mov_b32_e32 v95, v2
	v_mov_b32_e32 v96, v2
	v_mov_b32_e32 v97, v2
	v_mov_b32_e32 v110, v2
	v_mov_b32_e32 v111, v2
	v_mov_b32_e32 v112, v2
	v_mov_b32_e32 v113, v2
	v_mov_b32_e32 v114, v2
	v_mov_b32_e32 v115, v2
	v_mov_b32_e32 v116, v2
	v_mov_b32_e32 v117, v2
	v_mov_b32_e32 v126, v2
	v_mov_b32_e32 v127, v2
	v_mov_b32_e32 v128, v2
	v_mov_b32_e32 v129, v2
	v_mov_b32_e32 v138, v2
	v_mov_b32_e32 v139, v2
	v_mov_b32_e32 v140, v2
	v_mov_b32_e32 v141, v2
	v_readlane_b32 s46, v240, 14
	v_readlane_b32 s47, v240, 15
	v_readlane_b32 s48, v240, 19
	v_readlane_b32 s49, v240, 20
	s_barrier

.LBB0_1348:
	v_lshrrev_b32_e32 v18, 1, v6
	v_and_b32_e32 v145, 24, v18
	v_and_b32_e32 v9, 15, v6
	v_lshlrev_b32_e32 v18, 1, v145
	v_lshlrev_b32_e32 v6, 2, v6
	v_lshl_or_b32 v144, s10, 6, v9
	v_lshl_or_b32 v9, v9, 6, v18
	s_lshl_b32 s10, s10, 13
	v_and_b32_e32 v6, 32, v6
	v_lshl_add_u64 v[10:11], s[0:1], 0, v[172:173]
	v_mov_b32_e32 v135, v173
	v_bitop3_b32 v18, v9, s10, v6 bitop3:0xde
	s_lshl_b32 s10, s11, 5
	v_lshl_add_u64 v[12:13], s[0:1], 0, v[134:135]
	v_mov_b32_e32 v131, v173
	s_and_b32 s34, s10, 0x60
	s_add_i32 m0, s22, 0x18000
	v_lshl_add_u64 v[10:11], v[10:11], 0, s[84:85]
	v_lshl_add_u64 v[14:15], s[44:45], 0, v[130:131]
	v_mov_b32_e32 v133, v173
	s_lshl_b32 s10, s34, 7
	global_load_lds_dwordx4 v[10:11], off
	v_lshl_add_u64 v[10:11], v[12:13], 0, s[84:85]
	s_add_i32 m0, s22, 0x1a000
	s_add_i32 s35, s22, 0x8000
	s_add_i32 s38, s22, 0xa000
	v_lshl_add_u64 v[16:17], s[44:45], 0, v[132:133]
	v_bitop3_b32 v146, v9, s10, v6 bitop3:0xde
	global_load_lds_dwordx4 v[10:11], off
	v_lshl_add_u64 v[10:11], v[14:15], 0, s[84:85]
	s_mov_b32 m0, s35
	s_add_u32 s10, s0, 0x80080
	global_load_lds_dwordx4 v[10:11], off
	v_lshl_add_u64 v[10:11], v[16:17], 0, s[84:85]
	s_mov_b32 m0, s38
	s_addc_u32 s11, s1, 0
	global_load_lds_dwordx4 v[10:11], off
	s_add_i32 m0, s22, 0x1c000
	v_lshl_add_u64 v[10:11], s[10:11], 0, v[172:173]
	global_load_lds_dwordx4 v[10:11], off
	v_lshl_add_u64 v[10:11], s[10:11], 0, v[134:135]
	s_add_i32 m0, s22, 0x1e000
	v_lshlrev_b32_e32 v6, 15, v2
	global_load_lds_dwordx4 v[10:11], off
	s_waitcnt vmcnt(8)
	s_barrier
	v_and_b32_e32 v6, 0xffff0000, v6
	v_lshl_add_u32 v3, v3, 12, v6
	v_and_b32_e32 v2, 1, v2
	v_lshl_or_b32 v2, v2, 6, v3
	v_readlane_b32 s10, v240, 35
	v_lshl_add_u32 v2, v4, 1, v2
	v_mov_b32_e32 v3, v173
	v_readlane_b32 s11, v240, 36
	s_waitcnt vmcnt(6)
	s_mov_b32 s39, -2
	v_add_u32_e32 v147, 0, v18
	v_lshl_add_u64 v[136:137], s[10:11], 0, v[2:3]
	v_lshlrev_b32_e32 v2, 15, v5
	v_and_b32_e32 v2, 0xffff0000, v2
	v_lshl_add_u32 v2, v7, 12, v2
	v_and_b32_e32 v3, 1, v5
	v_lshl_or_b32 v2, v3, 6, v2
	v_lshl_add_u32 v2, v8, 1, v2
	v_mov_b32_e32 v3, v173
	v_lshl_add_u64 v[142:143], s[10:11], 0, v[2:3]
	v_mov_b32_e32 v2, 0
	s_mov_b64 s[10:11], 0
	v_mov_b32_e32 v3, v2
	v_mov_b32_e32 v4, v2
	v_mov_b32_e32 v5, v2
	v_mov_b32_e32 v6, v2
	v_mov_b32_e32 v7, v2
	v_mov_b32_e32 v8, v2
	v_mov_b32_e32 v9, v2
	v_mov_b32_e32 v18, v2
	v_mov_b32_e32 v19, v2
	v_mov_b32_e32 v20, v2
	v_mov_b32_e32 v21, v2
	v_mov_b32_e32 v22, v2
	v_mov_b32_e32 v23, v2
	v_mov_b32_e32 v24, v2
	v_mov_b32_e32 v25, v2
	v_mov_b32_e32 v34, v2
	v_mov_b32_e32 v35, v2
	v_mov_b32_e32 v36, v2
	v_mov_b32_e32 v37, v2
	v_mov_b32_e32 v38, v2
	v_mov_b32_e32 v39, v2
	v_mov_b32_e32 v40, v2
	v_mov_b32_e32 v41, v2
	v_mov_b32_e32 v50, v2
	v_mov_b32_e32 v51, v2
	v_mov_b32_e32 v52, v2
	v_mov_b32_e32 v53, v2
	v_mov_b32_e32 v54, v2
	v_mov_b32_e32 v55, v2
	v_mov_b32_e32 v56, v2
	v_mov_b32_e32 v57, v2
	v_mov_b32_e32 v10, v2
	v_mov_b32_e32 v11, v2
	v_mov_b32_e32 v12, v2
	v_mov_b32_e32 v13, v2
	v_mov_b32_e32 v14, v2
	v_mov_b32_e32 v15, v2
	v_mov_b32_e32 v16, v2
	v_mov_b32_e32 v17, v2
	v_mov_b32_e32 v26, v2
	v_mov_b32_e32 v27, v2
	v_mov_b32_e32 v28, v2
	v_mov_b32_e32 v29, v2
	v_mov_b32_e32 v30, v2
	v_mov_b32_e32 v31, v2
	v_mov_b32_e32 v32, v2
	v_mov_b32_e32 v33, v2
	v_mov_b32_e32 v42, v2
	v_mov_b32_e32 v43, v2
	v_mov_b32_e32 v44, v2
	v_mov_b32_e32 v45, v2
	v_mov_b32_e32 v46, v2
	v_mov_b32_e32 v47, v2
	v_mov_b32_e32 v48, v2
	v_mov_b32_e32 v49, v2
	v_mov_b32_e32 v58, v2
	v_mov_b32_e32 v59, v2
	v_mov_b32_e32 v60, v2
	v_mov_b32_e32 v61, v2
	v_mov_b32_e32 v62, v2
	v_mov_b32_e32 v63, v2
	v_mov_b32_e32 v64, v2
	v_mov_b32_e32 v65, v2
	v_mov_b32_e32 v66, v2
	v_mov_b32_e32 v67, v2
	v_mov_b32_e32 v68, v2
	v_mov_b32_e32 v69, v2
	v_mov_b32_e32 v70, v2
	v_mov_b32_e32 v71, v2
	v_mov_b32_e32 v72, v2
	v_mov_b32_e32 v73, v2
	v_mov_b32_e32 v82, v2
	v_mov_b32_e32 v83, v2
	v_mov_b32_e32 v84, v2
	v_mov_b32_e32 v85, v2
	v_mov_b32_e32 v86, v2
	v_mov_b32_e32 v87, v2
	v_mov_b32_e32 v88, v2
	v_mov_b32_e32 v89, v2
	v_mov_b32_e32 v102, v2
	v_mov_b32_e32 v103, v2
	v_mov_b32_e32 v104, v2
	v_mov_b32_e32 v105, v2
	v_mov_b32_e32 v106, v2
	v_mov_b32_e32 v107, v2
	v_mov_b32_e32 v108, v2
	v_mov_b32_e32 v109, v2
	v_mov_b32_e32 v118, v2
	v_mov_b32_e32 v119, v2
	v_mov_b32_e32 v120, v2
	v_mov_b32_e32 v121, v2
	v_mov_b32_e32 v122, v2
	v_mov_b32_e32 v123, v2
	v_mov_b32_e32 v124, v2
	v_mov_b32_e32 v125, v2
	v_mov_b32_e32 v74, v2
	v_mov_b32_e32 v75, v2
	v_mov_b32_e32 v76, v2
	v_mov_b32_e32 v77, v2
	v_mov_b32_e32 v78, v2
	v_mov_b32_e32 v79, v2
	v_mov_b32_e32 v80, v2
	v_mov_b32_e32 v81, v2
	v_mov_b32_e32 v90, v2
	v_mov_b32_e32 v91, v2
	v_mov_b32_e32 v92, v2
	v_mov_b32_e32 v93, v2
	v_mov_b32_e32 v94, v2
	v_mov_b32_e32 v95, v2
	v_mov_b32_e32 v96, v2
	v_mov_b32_e32 v97, v2
	v_mov_b32_e32 v110, v2
	v_mov_b32_e32 v111, v2
	v_mov_b32_e32 v112, v2
	v_mov_b32_e32 v113, v2
	v_mov_b32_e32 v114, v2
	v_mov_b32_e32 v115, v2
	v_mov_b32_e32 v116, v2
	v_mov_b32_e32 v117, v2
	v_mov_b32_e32 v126, v2
	v_mov_b32_e32 v127, v2
	v_mov_b32_e32 v128, v2
	v_mov_b32_e32 v129, v2
	v_mov_b32_e32 v138, v2
	v_mov_b32_e32 v139, v2
	v_mov_b32_e32 v140, v2
	v_mov_b32_e32 v141, v2
	v_readlane_b32 s46, v240, 33
	v_readlane_b32 s47, v240, 34
	v_readlane_b32 s48, v240, 38
	v_readlane_b32 s49, v240, 39
	s_barrier
